# hg_local + hg_out: gate-logit loads of hg_bcum issued together; hg_out V^T element loads issued back to back with one wait (were 8 groups of 4 loads each fully waited)
# speedup vs baseline: 1.0108x; 1.0047x over previous
; __device__ __forceinline__ float sigmoidf_(float x) { return 1.0f / (1.0f + __expf(-x)); }
; __device__ __forceinline__ void hg_bcum(const Params& p, int l, const u16* Uhg, int t0, int h, float* bc, float* lbs,
;                                         float* tots) {
;     ...
;   for (int k = 0; k < 4; ++k) {
;     const int s = (tid >> 4) + 16 * k, d0 = (tid & 15) * 8;
;     float z[8];
;     unpack8(*(const uint4*)(Uhg + (size_t)(t0 + s) * 2048 + 512 + h * 128 + d0), z);
;     float lf[8];
; #pragma unroll
;     for (int j = 0; j < 8; ++j) {
;       const float lbv = lbs[d0 + j];
;       const float f = lbv + (1.0f - lbv) * sigmoidf_(z[j]);
;       lf[j] = __logf(fmaxf(f, 1e-30f));
;     }
;     *(float4*)(bc + s * BCS + d0) = make_float4(lf[0], lf[1], lf[2], lf[3]);
;     *(float4*)(bc + s * BCS + d0 + 4) = make_float4(lf[4], lf[5], lf[6], lf[7]);
.LBB0_39:
	s_or_b64 exec, exec, s[0:1]
	s_and_b32 s12, s86, 0x7f
	s_lshl_b32 s0, s86, 4
	s_and_b32 s0, s0, 0xffffe000
	s_lshl_b32 s1, s12, 6
	s_or_b32 s13, s0, s1
	v_lshrrev_b32_e32 v59, 4, v34
	v_or_b32_e32 v46, s13, v59
	v_lshlrev_b32_e32 v34, 3, v50
	v_ashrrev_i32_e32 v47, 31, v46
	v_readlane_b32 s22, v252, 46
	v_and_b32_e32 v36, 0x78, v34
	v_lshlrev_b64 v[34:35], 12, v[46:47]
	v_readlane_b32 s23, v252, 47
	s_lshl_b32 s58, s20, 8
	v_lshlrev_b32_e32 v48, 1, v36
	v_lshl_add_u64 v[34:35], s[22:23], 0, v[34:35]
	v_lshl_add_u64 v[34:35], v[34:35], 0, s[58:59]
	v_mov_b32_e32 v49, v1
	v_lshl_add_u64 v[34:35], v[34:35], 0, v[48:49]
	s_waitcnt lgkmcnt(0)
	s_barrier
	v_lshl_add_u32 v64, v36, 2, s69
	s_mov_b32 s98, 0x10000
	s_mov_b32 s99, 0
	v_lshl_add_u64 v[110:111], v[34:35], 0, s[98:99]
	global_load_dwordx4 v[34:37], v[34:35], off offset:1024
	global_load_dwordx4 v[98:101], v[110:111], off offset:1024
	v_lshl_add_u64 v[110:111], v[110:111], 0, s[98:99]
	global_load_dwordx4 v[102:105], v[110:111], off offset:1024
	v_lshl_add_u64 v[110:111], v[110:111], 0, s[98:99]
	global_load_dwordx4 v[106:109], v[110:111], off offset:1024
	s_waitcnt vmcnt(3)
	v_lshlrev_b32_e32 v42, 16, v34
	v_mul_f32_e32 v42, 0xbfb8aa3b, v42
	v_exp_f32_e32 v42, v42
	v_and_b32_e32 v43, 0xffff0000, v34
	v_lshlrev_b32_e32 v44, 16, v35
	v_and_b32_e32 v45, 0xffff0000, v35
	v_add_f32_e32 v42, 1.0, v42
	v_div_scale_f32 v52, s[0:1], v42, v42, 1.0
	v_rcp_f32_e32 v53, v52
	v_lshlrev_b32_e32 v47, 16, v36
	v_and_b32_e32 v51, 0xffff0000, v36
	v_lshlrev_b32_e32 v62, 16, v37
	v_fma_f32 v54, -v52, v53, 1.0
	v_fmac_f32_e32 v53, v54, v53
	v_div_scale_f32 v54, vcc, 1.0, v42, 1.0
	v_mul_f32_e32 v55, v54, v53
	v_and_b32_e32 v63, 0xffff0000, v37
	ds_read_b128 v[38:41], v64 offset:33792
	ds_read_b128 v[34:37], v64 offset:33808
	v_fma_f32 v56, -v52, v55, v54
	v_fmac_f32_e32 v55, v56, v53
	v_fma_f32 v52, -v52, v55, v54
	v_div_fmas_f32 v52, v52, v53, v55
	s_waitcnt lgkmcnt(1)
	v_sub_f32_e32 v58, 1.0, v38
	v_div_fixup_f32 v42, v52, v42, 1.0
	v_fma_f32 v42, v58, v42, v38
	v_max_f32_e32 v42, 0xda24260, v42
	v_cmp_gt_f32_e32 vcc, s56, v42
	v_mul_f32_e32 v43, 0xbfb8aa3b, v43
	v_exp_f32_e32 v43, v43
	v_cndmask_b32_e64 v52, 0, 32, vcc
	v_ldexp_f32 v42, v42, v52
	v_log_f32_e32 v42, v42
	v_add_f32_e32 v43, 1.0, v43
	v_sub_f32_e32 v57, 1.0, v39
	v_mul_f32_e32 v44, 0xbfb8aa3b, v44
	v_mul_f32_e32 v52, 0x3f317217, v42
	v_fma_f32 v52, v42, s57, -v52
	v_fmac_f32_e32 v52, 0x3377d1cf, v42
	v_fmac_f32_e32 v52, 0x3f317217, v42
	v_cmp_lt_f32_e64 s[0:1], |v42|, s8
	v_exp_f32_e32 v44, v44
	v_mul_f32_e32 v45, 0xbfb8aa3b, v45
	v_cndmask_b32_e64 v42, v42, v52, s[0:1]
	v_cndmask_b32_e32 v52, 0, v201, vcc
	v_sub_f32_e32 v42, v42, v52
	v_div_scale_f32 v52, s[0:1], v43, v43, 1.0
	v_rcp_f32_e32 v53, v52
	v_add_f32_e32 v44, 1.0, v44
	v_exp_f32_e32 v45, v45
	v_mul_f32_e32 v47, 0xbfb8aa3b, v47
	v_fma_f32 v54, -v52, v53, 1.0
	v_fmac_f32_e32 v53, v54, v53
	v_div_scale_f32 v54, vcc, 1.0, v43, 1.0
	v_mul_f32_e32 v55, v54, v53
	v_fma_f32 v56, -v52, v55, v54
	v_fmac_f32_e32 v55, v56, v53
	v_fma_f32 v52, -v52, v55, v54
	v_div_fmas_f32 v52, v52, v53, v55
	v_div_fixup_f32 v43, v52, v43, 1.0
	v_fma_f32 v43, v43, v57, v39
	v_max_f32_e32 v43, 0xda24260, v43
	v_cmp_gt_f32_e32 vcc, s56, v43
	v_sub_f32_e32 v56, 1.0, v40
	v_add_f32_e32 v45, 1.0, v45
	v_cndmask_b32_e64 v52, 0, 32, vcc
	v_ldexp_f32 v43, v43, v52
	v_log_f32_e32 v43, v43
	v_exp_f32_e32 v47, v47
	v_mul_f32_e32 v52, 0x3f317217, v43
	v_fma_f32 v52, v43, s57, -v52
	v_fmac_f32_e32 v52, 0x3377d1cf, v43
	v_fmac_f32_e32 v52, 0x3f317217, v43
	v_cmp_lt_f32_e64 s[0:1], |v43|, s8
	v_add_f32_e32 v47, 1.0, v47
	s_nop 0
	v_cndmask_b32_e64 v43, v43, v52, s[0:1]
	v_cndmask_b32_e32 v52, 0, v201, vcc
	v_sub_f32_e32 v43, v43, v52
	v_div_scale_f32 v52, s[0:1], v44, v44, 1.0
	v_rcp_f32_e32 v53, v52
	s_nop 0
	v_fma_f32 v54, -v52, v53, 1.0
	v_fmac_f32_e32 v53, v54, v53
	v_div_scale_f32 v54, vcc, 1.0, v44, 1.0
	v_mul_f32_e32 v55, v54, v53
	v_fma_f32 v60, -v52, v55, v54
	v_fmac_f32_e32 v55, v60, v53
	v_fma_f32 v52, -v52, v55, v54
	v_div_fmas_f32 v52, v52, v53, v55
	v_div_fixup_f32 v44, v52, v44, 1.0
	v_fma_f32 v44, v44, v56, v40
	v_max_f32_e32 v44, 0xda24260, v44
	v_cmp_gt_f32_e32 vcc, s56, v44
	v_sub_f32_e32 v55, 1.0, v41
	s_nop 0
	v_cndmask_b32_e64 v52, 0, 32, vcc
	v_ldexp_f32 v44, v44, v52
	v_log_f32_e32 v44, v44
	s_nop 0
	v_mul_f32_e32 v52, 0x3f317217, v44
	v_fma_f32 v52, v44, s57, -v52
	v_fmac_f32_e32 v52, 0x3377d1cf, v44
	v_fmac_f32_e32 v52, 0x3f317217, v44
	v_cmp_lt_f32_e64 s[0:1], |v44|, s8
	s_nop 1
	v_cndmask_b32_e64 v44, v44, v52, s[0:1]
	v_cndmask_b32_e32 v52, 0, v201, vcc
	v_sub_f32_e32 v44, v44, v52
	v_div_scale_f32 v52, s[0:1], v45, v45, 1.0
	v_rcp_f32_e32 v53, v52
	s_nop 0
	v_fma_f32 v54, -v52, v53, 1.0
	v_fmac_f32_e32 v53, v54, v53
	v_div_scale_f32 v54, vcc, 1.0, v45, 1.0
	v_mul_f32_e32 v60, v54, v53
	v_fma_f32 v61, -v52, v60, v54
	v_fmac_f32_e32 v60, v61, v53
	v_fma_f32 v52, -v52, v60, v54
	v_div_fmas_f32 v52, v52, v53, v60
	v_div_fixup_f32 v45, v52, v45, 1.0
	v_fma_f32 v45, v45, v55, v41
	v_max_f32_e32 v45, 0xda24260, v45
	v_cmp_gt_f32_e32 vcc, s56, v45
	s_waitcnt lgkmcnt(0)
; __device__ __forceinline__ float sigmoidf_(float x) { return 1.0f / (1.0f + __expf(-x)); }
; __device__ __forceinline__ void hg_bcum(const Params& p, int l, const u16* Uhg, int t0, int h, float* bc, float* lbs,
;                                         float* tots) {
;     ...
;   for (int k = 0; k < 4; ++k) {
;     const int s = (tid >> 4) + 16 * k, d0 = (tid & 15) * 8;
;     float z[8];
;     unpack8(*(const uint4*)(Uhg + (size_t)(t0 + s) * 2048 + 512 + h * 128 + d0), z);
;     float lf[8];
; #pragma unroll
;     for (int j = 0; j < 8; ++j) {
;       const float lbv = lbs[d0 + j];
;       const float f = lbv + (1.0f - lbv) * sigmoidf_(z[j]);
;       lf[j] = __logf(fmaxf(f, 1e-30f));
;     }
;     *(float4*)(bc + s * BCS + d0) = make_float4(lf[0], lf[1], lf[2], lf[3]);
;     *(float4*)(bc + s * BCS + d0 + 4) = make_float4(lf[4], lf[5], lf[6], lf[7]);
	v_sub_f32_e32 v54, 1.0, v34
	v_cndmask_b32_e64 v52, 0, 32, vcc
	v_ldexp_f32 v45, v45, v52
	v_log_f32_e32 v45, v45
	s_nop 0
	v_mul_f32_e32 v52, 0x3f317217, v45
	v_fma_f32 v52, v45, s57, -v52
	v_fmac_f32_e32 v52, 0x3377d1cf, v45
	v_fmac_f32_e32 v52, 0x3f317217, v45
	v_cmp_lt_f32_e64 s[0:1], |v45|, s8
	s_nop 1
	v_cndmask_b32_e64 v45, v45, v52, s[0:1]
	v_cndmask_b32_e32 v52, 0, v201, vcc
	v_sub_f32_e32 v45, v45, v52
	v_div_scale_f32 v52, s[0:1], v47, v47, 1.0
	v_rcp_f32_e32 v53, v52
	s_nop 0
	v_fma_f32 v60, -v52, v53, 1.0
	v_fmac_f32_e32 v53, v60, v53
	v_div_scale_f32 v60, vcc, 1.0, v47, 1.0
	v_mul_f32_e32 v61, v60, v53
	v_fma_f32 v65, -v52, v61, v60
	v_fmac_f32_e32 v61, v65, v53
	v_fma_f32 v52, -v52, v61, v60
	v_div_fmas_f32 v52, v52, v53, v61
	v_div_fixup_f32 v47, v52, v47, 1.0
	v_fma_f32 v47, v47, v54, v34
	v_max_f32_e32 v47, 0xda24260, v47
	v_cmp_gt_f32_e32 vcc, s56, v47
	v_sub_f32_e32 v53, 1.0, v35
	s_nop 0
	v_cndmask_b32_e64 v52, 0, 32, vcc
	v_ldexp_f32 v47, v47, v52
	v_log_f32_e32 v47, v47
	s_nop 0
	v_mul_f32_e32 v52, 0x3f317217, v47
	v_fma_f32 v52, v47, s57, -v52
	v_fmac_f32_e32 v52, 0x3377d1cf, v47
	v_fmac_f32_e32 v52, 0x3f317217, v47
	v_cmp_lt_f32_e64 s[0:1], |v47|, s8
	s_nop 1
	v_cndmask_b32_e64 v47, v47, v52, s[0:1]
	v_cndmask_b32_e32 v52, 0, v201, vcc
	v_sub_f32_e32 v60, v47, v52
	v_mul_f32_e32 v47, 0xbfb8aa3b, v51
	v_exp_f32_e32 v47, v47
	s_nop 0
	v_add_f32_e32 v47, 1.0, v47
	v_div_scale_f32 v51, s[0:1], v47, v47, 1.0
	v_rcp_f32_e32 v52, v51
	s_nop 0
	v_fma_f32 v61, -v51, v52, 1.0
	v_fmac_f32_e32 v52, v61, v52
	v_div_scale_f32 v61, vcc, 1.0, v47, 1.0
	v_mul_f32_e32 v65, v61, v52
	v_fma_f32 v66, -v51, v65, v61
	v_fmac_f32_e32 v65, v66, v52
	v_fma_f32 v51, -v51, v65, v61
	v_div_fmas_f32 v51, v51, v52, v65
	v_div_fixup_f32 v47, v51, v47, 1.0
	v_fma_f32 v47, v47, v53, v35
	v_max_f32_e32 v47, 0xda24260, v47
	v_cmp_gt_f32_e32 vcc, s56, v47
	v_sub_f32_e32 v52, 1.0, v36
	s_nop 0
	v_cndmask_b32_e64 v51, 0, 32, vcc
	v_ldexp_f32 v47, v47, v51
	v_log_f32_e32 v47, v47
	s_nop 0
	v_mul_f32_e32 v51, 0x3f317217, v47
	v_fma_f32 v51, v47, s57, -v51
	v_fmac_f32_e32 v51, 0x3377d1cf, v47
	v_fmac_f32_e32 v51, 0x3f317217, v47
	v_cmp_lt_f32_e64 s[0:1], |v47|, s8
	s_nop 1
	v_cndmask_b32_e64 v47, v47, v51, s[0:1]
	v_cndmask_b32_e32 v51, 0, v201, vcc
	v_sub_f32_e32 v61, v47, v51
	v_mul_f32_e32 v47, 0xbfb8aa3b, v62
	v_exp_f32_e32 v47, v47
	s_nop 0
	v_add_f32_e32 v47, 1.0, v47
	v_div_scale_f32 v51, s[0:1], v47, v47, 1.0
	v_rcp_f32_e32 v62, v51
	s_nop 0
	v_fma_f32 v65, -v51, v62, 1.0
	v_fmac_f32_e32 v62, v65, v62
	v_div_scale_f32 v65, vcc, 1.0, v47, 1.0
	v_mul_f32_e32 v66, v65, v62
	v_fma_f32 v67, -v51, v66, v65
	v_fmac_f32_e32 v66, v67, v62
	v_fma_f32 v51, -v51, v66, v65
	v_div_fmas_f32 v51, v51, v62, v66
	v_div_fixup_f32 v47, v51, v47, 1.0
	v_fma_f32 v47, v47, v52, v36
	v_max_f32_e32 v47, 0xda24260, v47
	v_cmp_gt_f32_e32 vcc, s56, v47
	s_nop 1
	v_cndmask_b32_e64 v51, 0, 32, vcc
	v_ldexp_f32 v47, v47, v51
	v_log_f32_e32 v47, v47
	s_nop 0
	v_mul_f32_e32 v51, 0x3f317217, v47
	v_fma_f32 v51, v47, s57, -v51
	v_fmac_f32_e32 v51, 0x3377d1cf, v47
	v_fmac_f32_e32 v51, 0x3f317217, v47
	v_cmp_lt_f32_e64 s[0:1], |v47|, s8
	s_nop 1
	v_cndmask_b32_e64 v47, v47, v51, s[0:1]
	v_cndmask_b32_e32 v51, 0, v201, vcc
	v_sub_f32_e32 v62, v47, v51
	v_mul_f32_e32 v47, 0xbfb8aa3b, v63
	v_exp_f32_e32 v47, v47
	v_sub_f32_e32 v51, 1.0, v37
	v_add_f32_e32 v47, 1.0, v47
	v_div_scale_f32 v63, s[0:1], v47, v47, 1.0
	v_rcp_f32_e32 v65, v63
	s_nop 0
	v_fma_f32 v66, -v63, v65, 1.0
	v_fmac_f32_e32 v65, v66, v65
	v_div_scale_f32 v66, vcc, 1.0, v47, 1.0
	v_mul_f32_e32 v67, v66, v65
	v_fma_f32 v68, -v63, v67, v66
	v_fmac_f32_e32 v67, v68, v65
	v_fma_f32 v63, -v63, v67, v66
	v_div_fmas_f32 v63, v63, v65, v67
	v_div_fixup_f32 v47, v63, v47, 1.0
	v_fma_f32 v47, v47, v51, v37
	v_max_f32_e32 v47, 0xda24260, v47
	v_cmp_gt_f32_e32 vcc, s56, v47
	s_nop 1
	v_cndmask_b32_e64 v63, 0, 32, vcc
	v_ldexp_f32 v47, v47, v63
	v_log_f32_e32 v47, v47
	s_nop 0
	v_mul_f32_e32 v63, 0x3f317217, v47
	v_fma_f32 v63, v47, s57, -v63
	v_fmac_f32_e32 v63, 0x3377d1cf, v47
	v_fmac_f32_e32 v63, 0x3f317217, v47
	v_cmp_lt_f32_e64 s[0:1], |v47|, s8
	s_nop 1
	v_cndmask_b32_e64 v47, v47, v63, s[0:1]
	v_cndmask_b32_e32 v63, 0, v201, vcc
	v_sub_f32_e32 v63, v47, v63
	v_mad_u32_u24 v47, v59, s2, v64
	ds_write_b128 v47, v[42:45]
	ds_write_b128 v47, v[60:63] offset:16
	v_or_b32_e32 v42, 16, v46
	v_ashrrev_i32_e32 v43, 31, v42
	v_lshlrev_b64 v[42:43], 12, v[42:43]
	v_lshl_add_u64 v[42:43], s[22:23], 0, v[42:43]
	v_lshl_add_u64 v[42:43], v[42:43], 0, s[58:59]
	v_lshl_add_u64 v[42:43], v[42:43], 0, v[48:49]
	s_waitcnt vmcnt(2)
; __device__ __forceinline__ float sigmoidf_(float x) { return 1.0f / (1.0f + __expf(-x)); }
; __device__ __forceinline__ void hg_bcum(const Params& p, int l, const u16* Uhg, int t0, int h, float* bc, float* lbs,
;                                         float* tots) {
;     ...
;   for (int k = 0; k < 4; ++k) {
;     const int s = (tid >> 4) + 16 * k, d0 = (tid & 15) * 8;
;     float z[8];
;     unpack8(*(const uint4*)(Uhg + (size_t)(t0 + s) * 2048 + 512 + h * 128 + d0), z);
;     float lf[8];
; #pragma unroll
;     for (int j = 0; j < 8; ++j) {
;       const float lbv = lbs[d0 + j];
;       const float f = lbv + (1.0f - lbv) * sigmoidf_(z[j]);
;       lf[j] = __logf(fmaxf(f, 1e-30f));
;     }
;     *(float4*)(bc + s * BCS + d0) = make_float4(lf[0], lf[1], lf[2], lf[3]);
;     *(float4*)(bc + s * BCS + d0 + 4) = make_float4(lf[4], lf[5], lf[6], lf[7]);
	v_mov_b64_e32 v[42:43], v[98:99]
	v_mov_b64_e32 v[44:45], v[100:101]
	v_lshlrev_b32_e32 v61, 16, v42
	v_and_b32_e32 v62, 0xffff0000, v42
	v_mul_f32_e32 v42, 0xbfb8aa3b, v61
	v_exp_f32_e32 v42, v42
	v_lshlrev_b32_e32 v63, 16, v43
	v_and_b32_e32 v64, 0xffff0000, v43
	v_lshlrev_b32_e32 v65, 16, v44
	v_add_f32_e32 v42, 1.0, v42
	v_div_scale_f32 v43, s[0:1], v42, v42, 1.0
	v_and_b32_e32 v66, 0xffff0000, v44
	v_rcp_f32_e32 v44, v43
	v_lshlrev_b32_e32 v60, 16, v45
	v_and_b32_e32 v59, 0xffff0000, v45
	v_mul_f32_e32 v60, 0xbfb8aa3b, v60
	v_fma_f32 v45, -v43, v44, 1.0
	v_fmac_f32_e32 v44, v45, v44
	v_div_scale_f32 v45, vcc, 1.0, v42, 1.0
	v_mul_f32_e32 v61, v45, v44
	v_fma_f32 v67, -v43, v61, v45
	v_fmac_f32_e32 v61, v67, v44
	v_fma_f32 v43, -v43, v61, v45
	v_div_fmas_f32 v43, v43, v44, v61
	v_div_fixup_f32 v42, v43, v42, 1.0
	v_fma_f32 v42, v58, v42, v38
	v_max_f32_e32 v42, 0xda24260, v42
	v_cmp_gt_f32_e32 vcc, s56, v42
	v_exp_f32_e32 v60, v60
	v_mul_f32_e32 v59, 0xbfb8aa3b, v59
	v_cndmask_b32_e64 v43, 0, 32, vcc
	v_ldexp_f32 v42, v42, v43
	v_log_f32_e32 v42, v42
	v_add_f32_e32 v60, 1.0, v60
	v_exp_f32_e32 v59, v59
	v_mul_f32_e32 v43, 0x3f317217, v42
	v_fma_f32 v43, v42, s57, -v43
	v_fmac_f32_e32 v43, 0x3377d1cf, v42
	v_fmac_f32_e32 v43, 0x3f317217, v42
	v_cmp_lt_f32_e64 s[0:1], |v42|, s8
	v_add_f32_e32 v59, 1.0, v59
	s_nop 0
	v_cndmask_b32_e64 v42, v42, v43, s[0:1]
	v_cndmask_b32_e32 v43, 0, v201, vcc
	v_sub_f32_e32 v42, v42, v43
	v_mul_f32_e32 v43, 0xbfb8aa3b, v62
	v_exp_f32_e32 v43, v43
	s_nop 0
	v_add_f32_e32 v43, 1.0, v43
	v_div_scale_f32 v44, s[0:1], v43, v43, 1.0
	v_rcp_f32_e32 v45, v44
	s_nop 0
	v_fma_f32 v61, -v44, v45, 1.0
	v_fmac_f32_e32 v45, v61, v45
	v_div_scale_f32 v61, vcc, 1.0, v43, 1.0
	v_mul_f32_e32 v62, v61, v45
	v_fma_f32 v67, -v44, v62, v61
	v_fmac_f32_e32 v62, v67, v45
	v_fma_f32 v44, -v44, v62, v61
	v_div_fmas_f32 v44, v44, v45, v62
	v_div_fixup_f32 v43, v44, v43, 1.0
	v_fma_f32 v43, v57, v43, v39
	v_max_f32_e32 v43, 0xda24260, v43
	v_cmp_gt_f32_e32 vcc, s56, v43
	s_nop 1
	v_cndmask_b32_e64 v44, 0, 32, vcc
	v_ldexp_f32 v43, v43, v44
	v_log_f32_e32 v43, v43
	s_nop 0
	v_mul_f32_e32 v44, 0x3f317217, v43
	v_fma_f32 v44, v43, s57, -v44
	v_fmac_f32_e32 v44, 0x3377d1cf, v43
	v_fmac_f32_e32 v44, 0x3f317217, v43
	v_cmp_lt_f32_e64 s[0:1], |v43|, s8
	s_nop 1
	v_cndmask_b32_e64 v43, v43, v44, s[0:1]
	v_cndmask_b32_e32 v44, 0, v201, vcc
	v_sub_f32_e32 v43, v43, v44
	v_mul_f32_e32 v44, 0xbfb8aa3b, v63
	v_exp_f32_e32 v44, v44
	s_nop 0
	v_add_f32_e32 v44, 1.0, v44
	v_div_scale_f32 v45, s[0:1], v44, v44, 1.0
	v_rcp_f32_e32 v61, v45
	s_nop 0
	v_fma_f32 v62, -v45, v61, 1.0
	v_fmac_f32_e32 v61, v62, v61
	v_div_scale_f32 v62, vcc, 1.0, v44, 1.0
	v_mul_f32_e32 v63, v62, v61
	v_fma_f32 v67, -v45, v63, v62
	v_fmac_f32_e32 v63, v67, v61
	v_fma_f32 v45, -v45, v63, v62
	v_div_fmas_f32 v45, v45, v61, v63
	v_div_fixup_f32 v44, v45, v44, 1.0
	v_fma_f32 v44, v56, v44, v40
	v_max_f32_e32 v44, 0xda24260, v44
	v_cmp_gt_f32_e32 vcc, s56, v44
	s_nop 1
	v_cndmask_b32_e64 v45, 0, 32, vcc
	v_ldexp_f32 v44, v44, v45
	v_log_f32_e32 v44, v44
	s_nop 0
	v_mul_f32_e32 v45, 0x3f317217, v44
	v_fma_f32 v45, v44, s57, -v45
	v_fmac_f32_e32 v45, 0x3377d1cf, v44
	v_fmac_f32_e32 v45, 0x3f317217, v44
	v_cmp_lt_f32_e64 s[0:1], |v44|, s8
	s_nop 1
	v_cndmask_b32_e64 v44, v44, v45, s[0:1]
	v_cndmask_b32_e32 v45, 0, v201, vcc
	v_sub_f32_e32 v44, v44, v45
	v_mul_f32_e32 v45, 0xbfb8aa3b, v64
	v_exp_f32_e32 v45, v45
	s_nop 0
	v_add_f32_e32 v45, 1.0, v45
	v_div_scale_f32 v61, s[0:1], v45, v45, 1.0
	v_rcp_f32_e32 v62, v61
	s_nop 0
	v_fma_f32 v63, -v61, v62, 1.0
	v_fmac_f32_e32 v62, v63, v62
	v_div_scale_f32 v63, vcc, 1.0, v45, 1.0
	v_mul_f32_e32 v64, v63, v62
	v_fma_f32 v67, -v61, v64, v63
	v_fmac_f32_e32 v64, v67, v62
	v_fma_f32 v61, -v61, v64, v63
	v_div_fmas_f32 v61, v61, v62, v64
	v_div_fixup_f32 v45, v61, v45, 1.0
	v_fma_f32 v45, v55, v45, v41
	v_max_f32_e32 v45, 0xda24260, v45
	v_cmp_gt_f32_e32 vcc, s56, v45
	s_nop 1
	v_cndmask_b32_e64 v61, 0, 32, vcc
	v_ldexp_f32 v45, v45, v61
	v_log_f32_e32 v45, v45
	s_nop 0
	v_mul_f32_e32 v61, 0x3f317217, v45
	v_fma_f32 v61, v45, s57, -v61
	v_fmac_f32_e32 v61, 0x3377d1cf, v45
	v_fmac_f32_e32 v61, 0x3f317217, v45
	v_cmp_lt_f32_e64 s[0:1], |v45|, s8
	s_nop 1
	v_cndmask_b32_e64 v45, v45, v61, s[0:1]
	v_cndmask_b32_e32 v61, 0, v201, vcc
	v_sub_f32_e32 v45, v45, v61
	v_mul_f32_e32 v61, 0xbfb8aa3b, v65
	v_exp_f32_e32 v61, v61
	s_nop 0
	v_add_f32_e32 v61, 1.0, v61
	v_div_scale_f32 v62, s[0:1], v61, v61, 1.0
	v_rcp_f32_e32 v63, v62
	s_nop 0
	v_fma_f32 v64, -v62, v63, 1.0
	v_fmac_f32_e32 v63, v64, v63
	v_div_scale_f32 v64, vcc, 1.0, v61, 1.0
	v_mul_f32_e32 v65, v64, v63
	v_fma_f32 v67, -v62, v65, v64
	v_fmac_f32_e32 v65, v67, v63
	v_fma_f32 v62, -v62, v65, v64
	v_div_fmas_f32 v62, v62, v63, v65
	v_div_fixup_f32 v61, v62, v61, 1.0
	v_fma_f32 v61, v54, v61, v34
	v_max_f32_e32 v61, 0xda24260, v61
	v_cmp_gt_f32_e32 vcc, s56, v61
	s_nop 1
	v_cndmask_b32_e64 v62, 0, 32, vcc
	v_ldexp_f32 v61, v61, v62
	v_log_f32_e32 v61, v61
	s_nop 0
	v_mul_f32_e32 v62, 0x3f317217, v61
	v_fma_f32 v62, v61, s57, -v62
	v_fmac_f32_e32 v62, 0x3377d1cf, v61
	v_fmac_f32_e32 v62, 0x3f317217, v61
	v_cmp_lt_f32_e64 s[0:1], |v61|, s8
	s_nop 1
	v_cndmask_b32_e64 v61, v61, v62, s[0:1]
	v_cndmask_b32_e32 v62, 0, v201, vcc
	v_sub_f32_e32 v62, v61, v62
	v_mul_f32_e32 v61, 0xbfb8aa3b, v66
	v_exp_f32_e32 v61, v61
	s_nop 0
	v_add_f32_e32 v61, 1.0, v61
	v_div_scale_f32 v63, s[0:1], v61, v61, 1.0
	v_rcp_f32_e32 v64, v63
	s_nop 0
	v_fma_f32 v65, -v63, v64, 1.0
	v_fmac_f32_e32 v64, v65, v64
	v_div_scale_f32 v65, vcc, 1.0, v61, 1.0
	v_mul_f32_e32 v66, v65, v64
	v_fma_f32 v67, -v63, v66, v65
; __device__ __forceinline__ float sigmoidf_(float x) { return 1.0f / (1.0f + __expf(-x)); }
; __device__ __forceinline__ void hg_bcum(const Params& p, int l, const u16* Uhg, int t0, int h, float* bc, float* lbs,
;                                         float* tots) {
;     ...
;   for (int k = 0; k < 4; ++k) {
;     const int s = (tid >> 4) + 16 * k, d0 = (tid & 15) * 8;
;     float z[8];
;     unpack8(*(const uint4*)(Uhg + (size_t)(t0 + s) * 2048 + 512 + h * 128 + d0), z);
;     float lf[8];
; #pragma unroll
;     for (int j = 0; j < 8; ++j) {
;       const float lbv = lbs[d0 + j];
;       const float f = lbv + (1.0f - lbv) * sigmoidf_(z[j]);
;       lf[j] = __logf(fmaxf(f, 1e-30f));
;     }
;     *(float4*)(bc + s * BCS + d0) = make_float4(lf[0], lf[1], lf[2], lf[3]);
;     *(float4*)(bc + s * BCS + d0 + 4) = make_float4(lf[4], lf[5], lf[6], lf[7]);
	v_fmac_f32_e32 v66, v67, v64
	v_fma_f32 v63, -v63, v66, v65
	v_div_fmas_f32 v63, v63, v64, v66
	v_div_fixup_f32 v61, v63, v61, 1.0
	v_fma_f32 v61, v53, v61, v35
	v_max_f32_e32 v61, 0xda24260, v61
	v_cmp_gt_f32_e32 vcc, s56, v61
	s_nop 1
	v_cndmask_b32_e64 v63, 0, 32, vcc
	v_ldexp_f32 v61, v61, v63
	v_log_f32_e32 v61, v61
	s_nop 0
	v_mul_f32_e32 v63, 0x3f317217, v61
	v_fma_f32 v63, v61, s57, -v63
	v_fmac_f32_e32 v63, 0x3377d1cf, v61
	v_fmac_f32_e32 v63, 0x3f317217, v61
	v_cmp_lt_f32_e64 s[0:1], |v61|, s8
	s_nop 1
	v_cndmask_b32_e64 v61, v61, v63, s[0:1]
	v_cndmask_b32_e32 v63, 0, v201, vcc
	v_sub_f32_e32 v63, v61, v63
	v_div_scale_f32 v61, s[0:1], v60, v60, 1.0
	v_rcp_f32_e32 v64, v61
	s_nop 0
	v_fma_f32 v65, -v61, v64, 1.0
	v_fmac_f32_e32 v64, v65, v64
	v_div_scale_f32 v65, vcc, 1.0, v60, 1.0
	v_mul_f32_e32 v66, v65, v64
	v_fma_f32 v67, -v61, v66, v65
	v_fmac_f32_e32 v66, v67, v64
	v_fma_f32 v61, -v61, v66, v65
	v_div_fmas_f32 v61, v61, v64, v66
	v_div_fixup_f32 v60, v61, v60, 1.0
	v_fma_f32 v60, v52, v60, v36
	v_max_f32_e32 v60, 0xda24260, v60
	v_cmp_gt_f32_e32 vcc, s56, v60
	s_nop 1
	v_cndmask_b32_e64 v61, 0, 32, vcc
	v_ldexp_f32 v60, v60, v61
	v_log_f32_e32 v60, v60
	s_nop 0
	v_mul_f32_e32 v61, 0x3f317217, v60
	v_fma_f32 v61, v60, s57, -v61
	v_fmac_f32_e32 v61, 0x3377d1cf, v60
	v_fmac_f32_e32 v61, 0x3f317217, v60
	v_cmp_lt_f32_e64 s[0:1], |v60|, s8
	s_nop 1
	v_cndmask_b32_e64 v60, v60, v61, s[0:1]
	v_cndmask_b32_e32 v61, 0, v201, vcc
	v_sub_f32_e32 v64, v60, v61
	v_div_scale_f32 v60, s[0:1], v59, v59, 1.0
	v_rcp_f32_e32 v61, v60
	s_nop 0
	v_fma_f32 v65, -v60, v61, 1.0
	v_fmac_f32_e32 v61, v65, v61
	v_div_scale_f32 v65, vcc, 1.0, v59, 1.0
	v_mul_f32_e32 v66, v65, v61
	v_fma_f32 v67, -v60, v66, v65
	v_fmac_f32_e32 v66, v67, v61
	v_fma_f32 v60, -v60, v66, v65
	v_div_fmas_f32 v60, v60, v61, v66
	v_div_fixup_f32 v59, v60, v59, 1.0
	v_fma_f32 v59, v51, v59, v37
	v_max_f32_e32 v59, 0xda24260, v59
	v_cmp_gt_f32_e32 vcc, s56, v59
	s_nop 1
	v_cndmask_b32_e64 v60, 0, 32, vcc
	v_ldexp_f32 v59, v59, v60
	v_log_f32_e32 v59, v59
	s_nop 0
	v_mul_f32_e32 v60, 0x3f317217, v59
	v_fma_f32 v60, v59, s57, -v60
	v_fmac_f32_e32 v60, 0x3377d1cf, v59
	v_fmac_f32_e32 v60, 0x3f317217, v59
	v_cmp_lt_f32_e64 s[0:1], |v59|, s8
	s_nop 1
	v_cndmask_b32_e64 v59, v59, v60, s[0:1]
	v_cndmask_b32_e32 v60, 0, v201, vcc
	v_sub_f32_e32 v65, v59, v60
	ds_write_b128 v47, v[42:45] offset:8448
	ds_write_b128 v47, v[62:65] offset:8464
	v_or_b32_e32 v42, 32, v46
	v_ashrrev_i32_e32 v43, 31, v42
	v_lshlrev_b64 v[42:43], 12, v[42:43]
	v_lshl_add_u64 v[42:43], s[22:23], 0, v[42:43]
	v_lshl_add_u64 v[42:43], v[42:43], 0, s[58:59]
	v_lshl_add_u64 v[42:43], v[42:43], 0, v[48:49]
	s_waitcnt vmcnt(1)
	v_mov_b64_e32 v[42:43], v[102:103]
	v_mov_b64_e32 v[44:45], v[104:105]
	v_lshlrev_b32_e32 v59, 16, v42
	v_and_b32_e32 v60, 0xffff0000, v42
	v_mul_f32_e32 v42, 0xbfb8aa3b, v59
	v_exp_f32_e32 v42, v42
	v_lshlrev_b32_e32 v61, 16, v43
	v_and_b32_e32 v62, 0xffff0000, v43
	v_lshlrev_b32_e32 v63, 16, v44
	v_add_f32_e32 v42, 1.0, v42
	v_div_scale_f32 v43, s[0:1], v42, v42, 1.0
	v_and_b32_e32 v64, 0xffff0000, v44
	v_rcp_f32_e32 v44, v43
	v_lshlrev_b32_e32 v65, 16, v45
	v_and_b32_e32 v66, 0xffff0000, v45
	v_fma_f32 v45, -v43, v44, 1.0
	v_fmac_f32_e32 v44, v45, v44
	v_div_scale_f32 v45, vcc, 1.0, v42, 1.0
	v_mul_f32_e32 v59, v45, v44
	v_fma_f32 v67, -v43, v59, v45
	v_fmac_f32_e32 v59, v67, v44
	v_fma_f32 v43, -v43, v59, v45
	v_div_fmas_f32 v43, v43, v44, v59
	v_div_fixup_f32 v42, v43, v42, 1.0
	v_fma_f32 v42, v58, v42, v38
	v_max_f32_e32 v42, 0xda24260, v42
	v_cmp_gt_f32_e32 vcc, s56, v42
	s_nop 1
	v_cndmask_b32_e64 v43, 0, 32, vcc
	v_ldexp_f32 v42, v42, v43
	v_log_f32_e32 v42, v42
	s_nop 0
	v_mul_f32_e32 v43, 0x3f317217, v42
	v_fma_f32 v43, v42, s57, -v43
	v_fmac_f32_e32 v43, 0x3377d1cf, v42
	v_fmac_f32_e32 v43, 0x3f317217, v42
	v_cmp_lt_f32_e64 s[0:1], |v42|, s8
	s_nop 1
	v_cndmask_b32_e64 v42, v42, v43, s[0:1]
	v_cndmask_b32_e32 v43, 0, v201, vcc
	v_sub_f32_e32 v42, v42, v43
	v_mul_f32_e32 v43, 0xbfb8aa3b, v60
	v_exp_f32_e32 v43, v43
	s_nop 0
	v_add_f32_e32 v43, 1.0, v43
	v_div_scale_f32 v44, s[0:1], v43, v43, 1.0
	v_rcp_f32_e32 v45, v44
	s_nop 0
	v_fma_f32 v59, -v44, v45, 1.0
	v_fmac_f32_e32 v45, v59, v45
	v_div_scale_f32 v59, vcc, 1.0, v43, 1.0
	v_mul_f32_e32 v60, v59, v45
	v_fma_f32 v67, -v44, v60, v59
	v_fmac_f32_e32 v60, v67, v45
	v_fma_f32 v44, -v44, v60, v59
	v_div_fmas_f32 v44, v44, v45, v60
	v_div_fixup_f32 v43, v44, v43, 1.0
	v_fma_f32 v43, v57, v43, v39
	v_max_f32_e32 v43, 0xda24260, v43
	v_cmp_gt_f32_e32 vcc, s56, v43
	s_nop 1
	v_cndmask_b32_e64 v44, 0, 32, vcc
	v_ldexp_f32 v43, v43, v44
	v_log_f32_e32 v43, v43
	s_nop 0
	v_mul_f32_e32 v44, 0x3f317217, v43
	v_fma_f32 v44, v43, s57, -v44
	v_fmac_f32_e32 v44, 0x3377d1cf, v43
	v_fmac_f32_e32 v44, 0x3f317217, v43
	v_cmp_lt_f32_e64 s[0:1], |v43|, s8
	s_nop 1
	v_cndmask_b32_e64 v43, v43, v44, s[0:1]
	v_cndmask_b32_e32 v44, 0, v201, vcc
	v_sub_f32_e32 v43, v43, v44
	v_mul_f32_e32 v44, 0xbfb8aa3b, v61
	v_exp_f32_e32 v44, v44
	s_nop 0
	v_add_f32_e32 v44, 1.0, v44
	v_div_scale_f32 v45, s[0:1], v44, v44, 1.0
	v_rcp_f32_e32 v59, v45
	s_nop 0
	v_fma_f32 v60, -v45, v59, 1.0
	v_fmac_f32_e32 v59, v60, v59
	v_div_scale_f32 v60, vcc, 1.0, v44, 1.0
	v_mul_f32_e32 v61, v60, v59
	v_fma_f32 v67, -v45, v61, v60
	v_fmac_f32_e32 v61, v67, v59
	v_fma_f32 v45, -v45, v61, v60
	v_div_fmas_f32 v45, v45, v59, v61
	v_div_fixup_f32 v44, v45, v44, 1.0
	v_fma_f32 v44, v56, v44, v40
	v_max_f32_e32 v44, 0xda24260, v44
	v_cmp_gt_f32_e32 vcc, s56, v44
	s_nop 1
	v_cndmask_b32_e64 v45, 0, 32, vcc
	v_ldexp_f32 v44, v44, v45
	v_log_f32_e32 v44, v44
	s_nop 0
	v_mul_f32_e32 v45, 0x3f317217, v44
; __device__ __forceinline__ float sigmoidf_(float x) { return 1.0f / (1.0f + __expf(-x)); }
; __device__ __forceinline__ void hg_bcum(const Params& p, int l, const u16* Uhg, int t0, int h, float* bc, float* lbs,
;                                         float* tots) {
;     ...
;   for (int k = 0; k < 4; ++k) {
;     const int s = (tid >> 4) + 16 * k, d0 = (tid & 15) * 8;
;     float z[8];
;     unpack8(*(const uint4*)(Uhg + (size_t)(t0 + s) * 2048 + 512 + h * 128 + d0), z);
;     float lf[8];
; #pragma unroll
;     for (int j = 0; j < 8; ++j) {
;       const float lbv = lbs[d0 + j];
;       const float f = lbv + (1.0f - lbv) * sigmoidf_(z[j]);
;       lf[j] = __logf(fmaxf(f, 1e-30f));
;     }
;     *(float4*)(bc + s * BCS + d0) = make_float4(lf[0], lf[1], lf[2], lf[3]);
;     *(float4*)(bc + s * BCS + d0 + 4) = make_float4(lf[4], lf[5], lf[6], lf[7]);
	v_fma_f32 v45, v44, s57, -v45
	v_fmac_f32_e32 v45, 0x3377d1cf, v44
	v_fmac_f32_e32 v45, 0x3f317217, v44
	v_cmp_lt_f32_e64 s[0:1], |v44|, s8
	s_nop 1
	v_cndmask_b32_e64 v44, v44, v45, s[0:1]
	v_cndmask_b32_e32 v45, 0, v201, vcc
	v_sub_f32_e32 v44, v44, v45
	v_mul_f32_e32 v45, 0xbfb8aa3b, v62
	v_exp_f32_e32 v45, v45
	s_nop 0
	v_add_f32_e32 v45, 1.0, v45
	v_div_scale_f32 v59, s[0:1], v45, v45, 1.0
	v_rcp_f32_e32 v60, v59
	s_nop 0
	v_fma_f32 v61, -v59, v60, 1.0
	v_fmac_f32_e32 v60, v61, v60
	v_div_scale_f32 v61, vcc, 1.0, v45, 1.0
	v_mul_f32_e32 v62, v61, v60
	v_fma_f32 v67, -v59, v62, v61
	v_fmac_f32_e32 v62, v67, v60
	v_fma_f32 v59, -v59, v62, v61
	v_div_fmas_f32 v59, v59, v60, v62
	v_div_fixup_f32 v45, v59, v45, 1.0
	v_fma_f32 v45, v55, v45, v41
	v_max_f32_e32 v45, 0xda24260, v45
	v_cmp_gt_f32_e32 vcc, s56, v45
	s_nop 1
	v_cndmask_b32_e64 v59, 0, 32, vcc
	v_ldexp_f32 v45, v45, v59
	v_log_f32_e32 v45, v45
	s_nop 0
	v_mul_f32_e32 v59, 0x3f317217, v45
	v_fma_f32 v59, v45, s57, -v59
	v_fmac_f32_e32 v59, 0x3377d1cf, v45
	v_fmac_f32_e32 v59, 0x3f317217, v45
	v_cmp_lt_f32_e64 s[0:1], |v45|, s8
	s_nop 1
	v_cndmask_b32_e64 v45, v45, v59, s[0:1]
	v_cndmask_b32_e32 v59, 0, v201, vcc
	v_sub_f32_e32 v45, v45, v59
	v_mul_f32_e32 v59, 0xbfb8aa3b, v63
	v_exp_f32_e32 v59, v59
	s_nop 0
	v_add_f32_e32 v59, 1.0, v59
	v_div_scale_f32 v60, s[0:1], v59, v59, 1.0
	v_rcp_f32_e32 v61, v60
	s_nop 0
	v_fma_f32 v62, -v60, v61, 1.0
	v_fmac_f32_e32 v61, v62, v61
	v_div_scale_f32 v62, vcc, 1.0, v59, 1.0
	v_mul_f32_e32 v63, v62, v61
	v_fma_f32 v67, -v60, v63, v62
	v_fmac_f32_e32 v63, v67, v61
	v_fma_f32 v60, -v60, v63, v62
	v_div_fmas_f32 v60, v60, v61, v63
	v_div_fixup_f32 v59, v60, v59, 1.0
	v_fma_f32 v59, v54, v59, v34
	v_max_f32_e32 v59, 0xda24260, v59
	v_cmp_gt_f32_e32 vcc, s56, v59
	s_nop 1
	v_cndmask_b32_e64 v60, 0, 32, vcc
	v_ldexp_f32 v59, v59, v60
	v_log_f32_e32 v59, v59
	s_nop 0
	v_mul_f32_e32 v60, 0x3f317217, v59
	v_fma_f32 v60, v59, s57, -v60
	v_fmac_f32_e32 v60, 0x3377d1cf, v59
	v_fmac_f32_e32 v60, 0x3f317217, v59
	v_cmp_lt_f32_e64 s[0:1], |v59|, s8
	s_nop 1
	v_cndmask_b32_e64 v59, v59, v60, s[0:1]
	v_cndmask_b32_e32 v60, 0, v201, vcc
	v_sub_f32_e32 v60, v59, v60
	v_mul_f32_e32 v59, 0xbfb8aa3b, v64
	v_exp_f32_e32 v59, v59
	s_nop 0
	v_add_f32_e32 v59, 1.0, v59
	v_div_scale_f32 v61, s[0:1], v59, v59, 1.0
	v_rcp_f32_e32 v62, v61
	s_nop 0
	v_fma_f32 v63, -v61, v62, 1.0
	v_fmac_f32_e32 v62, v63, v62
	v_div_scale_f32 v63, vcc, 1.0, v59, 1.0
	v_mul_f32_e32 v64, v63, v62
	v_fma_f32 v67, -v61, v64, v63
	v_fmac_f32_e32 v64, v67, v62
	v_fma_f32 v61, -v61, v64, v63
	v_div_fmas_f32 v61, v61, v62, v64
	v_div_fixup_f32 v59, v61, v59, 1.0
	v_fma_f32 v59, v53, v59, v35
	v_max_f32_e32 v59, 0xda24260, v59
	v_cmp_gt_f32_e32 vcc, s56, v59
	s_nop 1
	v_cndmask_b32_e64 v61, 0, 32, vcc
	v_ldexp_f32 v59, v59, v61
	v_log_f32_e32 v59, v59
	s_nop 0
	v_mul_f32_e32 v61, 0x3f317217, v59
	v_fma_f32 v61, v59, s57, -v61
	v_fmac_f32_e32 v61, 0x3377d1cf, v59
	v_fmac_f32_e32 v61, 0x3f317217, v59
	v_cmp_lt_f32_e64 s[0:1], |v59|, s8
	s_nop 1
	v_cndmask_b32_e64 v59, v59, v61, s[0:1]
	v_cndmask_b32_e32 v61, 0, v201, vcc
	v_sub_f32_e32 v61, v59, v61
	v_mul_f32_e32 v59, 0xbfb8aa3b, v65
	v_exp_f32_e32 v59, v59
	s_nop 0
	v_add_f32_e32 v59, 1.0, v59
	v_div_scale_f32 v62, s[0:1], v59, v59, 1.0
	v_rcp_f32_e32 v63, v62
	s_nop 0
	v_fma_f32 v64, -v62, v63, 1.0
	v_fmac_f32_e32 v63, v64, v63
	v_div_scale_f32 v64, vcc, 1.0, v59, 1.0
	v_mul_f32_e32 v65, v64, v63
	v_fma_f32 v67, -v62, v65, v64
	v_fmac_f32_e32 v65, v67, v63
	v_fma_f32 v62, -v62, v65, v64
	v_div_fmas_f32 v62, v62, v63, v65
	v_div_fixup_f32 v59, v62, v59, 1.0
	v_fma_f32 v59, v52, v59, v36
	v_max_f32_e32 v59, 0xda24260, v59
	v_cmp_gt_f32_e32 vcc, s56, v59
	s_nop 1
	v_cndmask_b32_e64 v62, 0, 32, vcc
	v_ldexp_f32 v59, v59, v62
	v_log_f32_e32 v59, v59
	s_nop 0
	v_mul_f32_e32 v62, 0x3f317217, v59
	v_fma_f32 v62, v59, s57, -v62
	v_fmac_f32_e32 v62, 0x3377d1cf, v59
	v_fmac_f32_e32 v62, 0x3f317217, v59
	v_cmp_lt_f32_e64 s[0:1], |v59|, s8
	s_nop 1
	v_cndmask_b32_e64 v59, v59, v62, s[0:1]
	v_cndmask_b32_e32 v62, 0, v201, vcc
	v_sub_f32_e32 v62, v59, v62
	v_mul_f32_e32 v59, 0xbfb8aa3b, v66
	v_exp_f32_e32 v59, v59
	s_nop 0
	v_add_f32_e32 v59, 1.0, v59
	v_div_scale_f32 v63, s[0:1], v59, v59, 1.0
	v_rcp_f32_e32 v64, v63
	s_nop 0
	v_fma_f32 v65, -v63, v64, 1.0
	v_fmac_f32_e32 v64, v65, v64
	v_div_scale_f32 v65, vcc, 1.0, v59, 1.0
	v_mul_f32_e32 v66, v65, v64
	v_fma_f32 v67, -v63, v66, v65
	v_fmac_f32_e32 v66, v67, v64
	v_fma_f32 v63, -v63, v66, v65
	v_div_fmas_f32 v63, v63, v64, v66
	v_div_fixup_f32 v59, v63, v59, 1.0
	v_fma_f32 v59, v51, v59, v37
	v_max_f32_e32 v59, 0xda24260, v59
	v_cmp_gt_f32_e32 vcc, s56, v59
	s_nop 1
	v_cndmask_b32_e64 v63, 0, 32, vcc
	v_ldexp_f32 v59, v59, v63
	v_log_f32_e32 v59, v59
	s_nop 0
	v_mul_f32_e32 v63, 0x3f317217, v59
	v_fma_f32 v63, v59, s57, -v63
	v_fmac_f32_e32 v63, 0x3377d1cf, v59
	v_fmac_f32_e32 v63, 0x3f317217, v59
	v_cmp_lt_f32_e64 s[0:1], |v59|, s8
	s_nop 1
	v_cndmask_b32_e64 v59, v59, v63, s[0:1]
	v_cndmask_b32_e32 v63, 0, v201, vcc
	v_sub_f32_e32 v63, v59, v63
	ds_write_b128 v47, v[42:45] offset:16896
	ds_write_b128 v47, v[60:63] offset:16912
	v_or_b32_e32 v42, 48, v46
	v_ashrrev_i32_e32 v43, 31, v42
	v_lshlrev_b64 v[42:43], 12, v[42:43]
	v_lshl_add_u64 v[42:43], s[22:23], 0, v[42:43]
	v_lshl_add_u64 v[42:43], v[42:43], 0, s[58:59]
	v_lshl_add_u64 v[42:43], v[42:43], 0, v[48:49]
	s_waitcnt vmcnt(0)
; __device__ __forceinline__ float sigmoidf_(float x) { return 1.0f / (1.0f + __expf(-x)); }
; __device__ __forceinline__ void hg_bcum(const Params& p, int l, const u16* Uhg, int t0, int h, float* bc, float* lbs,
;                                         float* tots) {
;     ...
;   for (int k = 0; k < 4; ++k) {
;     const int s = (tid >> 4) + 16 * k, d0 = (tid & 15) * 8;
;     float z[8];
;     unpack8(*(const uint4*)(Uhg + (size_t)(t0 + s) * 2048 + 512 + h * 128 + d0), z);
;     float lf[8];
; #pragma unroll
;     for (int j = 0; j < 8; ++j) {
;       const float lbv = lbs[d0 + j];
;       const float f = lbv + (1.0f - lbv) * sigmoidf_(z[j]);
;       lf[j] = __logf(fmaxf(f, 1e-30f));
;     }
;     *(float4*)(bc + s * BCS + d0) = make_float4(lf[0], lf[1], lf[2], lf[3]);
;     *(float4*)(bc + s * BCS + d0 + 4) = make_float4(lf[4], lf[5], lf[6], lf[7]);
	v_mov_b64_e32 v[42:43], v[106:107]
	v_mov_b64_e32 v[44:45], v[108:109]
	v_lshlrev_b32_e32 v46, 16, v42
	v_and_b32_e32 v48, 0xffff0000, v42
	v_lshlrev_b32_e32 v49, 16, v43
	v_and_b32_e32 v59, 0xffff0000, v43
	v_lshlrev_b32_e32 v43, 16, v45
	v_and_b32_e32 v42, 0xffff0000, v45
	v_mul_f32_e32 v45, 0xbfb8aa3b, v46
	v_exp_f32_e32 v45, v45
	v_lshlrev_b32_e32 v60, 16, v44
	v_and_b32_e32 v44, 0xffff0000, v44
	v_mul_f32_e32 v44, 0xbfb8aa3b, v44
	v_add_f32_e32 v45, 1.0, v45
	v_div_scale_f32 v46, s[0:1], v45, v45, 1.0
	v_rcp_f32_e32 v61, v46
	v_exp_f32_e32 v44, v44
	v_mul_f32_e32 v43, 0xbfb8aa3b, v43
	v_exp_f32_e32 v43, v43
	v_fma_f32 v62, -v46, v61, 1.0
	v_fmac_f32_e32 v61, v62, v61
	v_div_scale_f32 v62, vcc, 1.0, v45, 1.0
	v_mul_f32_e32 v63, v62, v61
	v_fma_f32 v64, -v46, v63, v62
	v_fmac_f32_e32 v63, v64, v61
	v_fma_f32 v46, -v46, v63, v62
	v_div_fmas_f32 v46, v46, v61, v63
	v_div_fixup_f32 v45, v46, v45, 1.0
	v_fma_f32 v38, v58, v45, v38
	v_max_f32_e32 v38, 0xda24260, v38
	v_cmp_gt_f32_e32 vcc, s56, v38
	v_add_f32_e32 v44, 1.0, v44
	v_add_f32_e32 v43, 1.0, v43
	v_cndmask_b32_e64 v45, 0, 32, vcc
	v_ldexp_f32 v38, v38, v45
	v_log_f32_e32 v38, v38
	v_mul_f32_e32 v42, 0xbfb8aa3b, v42
	v_exp_f32_e32 v42, v42
	v_mul_f32_e32 v45, 0x3f317217, v38
	v_fma_f32 v45, v38, s57, -v45
	v_fmac_f32_e32 v45, 0x3377d1cf, v38
	v_fmac_f32_e32 v45, 0x3f317217, v38
	v_cmp_lt_f32_e64 s[0:1], |v38|, s8
	v_add_f32_e32 v42, 1.0, v42
	s_nop 0
	v_cndmask_b32_e64 v38, v38, v45, s[0:1]
	v_cndmask_b32_e32 v45, 0, v201, vcc
	v_sub_f32_e32 v38, v38, v45
	v_mul_f32_e32 v45, 0xbfb8aa3b, v48
	v_exp_f32_e32 v45, v45
	s_nop 0
	v_add_f32_e32 v45, 1.0, v45
	v_div_scale_f32 v46, s[0:1], v45, v45, 1.0
	v_rcp_f32_e32 v48, v46
	s_nop 0
	v_fma_f32 v58, -v46, v48, 1.0
	v_fmac_f32_e32 v48, v58, v48
	v_div_scale_f32 v58, vcc, 1.0, v45, 1.0
	v_mul_f32_e32 v61, v58, v48
	v_fma_f32 v62, -v46, v61, v58
	v_fmac_f32_e32 v61, v62, v48
	v_fma_f32 v46, -v46, v61, v58
	v_div_fmas_f32 v46, v46, v48, v61
	v_div_fixup_f32 v45, v46, v45, 1.0
	v_fma_f32 v39, v57, v45, v39
	v_max_f32_e32 v39, 0xda24260, v39
	v_cmp_gt_f32_e32 vcc, s56, v39
	s_nop 1
	v_cndmask_b32_e64 v45, 0, 32, vcc
	v_ldexp_f32 v39, v39, v45
	v_log_f32_e32 v39, v39
	s_nop 0
	v_mul_f32_e32 v45, 0x3f317217, v39
	v_fma_f32 v45, v39, s57, -v45
	v_fmac_f32_e32 v45, 0x3377d1cf, v39
	v_fmac_f32_e32 v45, 0x3f317217, v39
	v_cmp_lt_f32_e64 s[0:1], |v39|, s8
	s_nop 1
	v_cndmask_b32_e64 v39, v39, v45, s[0:1]
	v_cndmask_b32_e32 v45, 0, v201, vcc
	v_sub_f32_e32 v39, v39, v45
	v_mul_f32_e32 v45, 0xbfb8aa3b, v49
	v_exp_f32_e32 v45, v45
	s_nop 0
	v_add_f32_e32 v45, 1.0, v45
	v_div_scale_f32 v46, s[0:1], v45, v45, 1.0
	v_rcp_f32_e32 v48, v46
	s_nop 0
	v_fma_f32 v49, -v46, v48, 1.0
	v_fmac_f32_e32 v48, v49, v48
	v_div_scale_f32 v49, vcc, 1.0, v45, 1.0
	v_mul_f32_e32 v57, v49, v48
	v_fma_f32 v58, -v46, v57, v49
	v_fmac_f32_e32 v57, v58, v48
	v_fma_f32 v46, -v46, v57, v49
	v_div_fmas_f32 v46, v46, v48, v57
	v_div_fixup_f32 v45, v46, v45, 1.0
	v_fma_f32 v40, v56, v45, v40
	v_max_f32_e32 v40, 0xda24260, v40
	v_cmp_gt_f32_e32 vcc, s56, v40
	s_nop 1
	v_cndmask_b32_e64 v45, 0, 32, vcc
	v_ldexp_f32 v40, v40, v45
	v_log_f32_e32 v40, v40
	s_nop 0
	v_mul_f32_e32 v45, 0x3f317217, v40
	v_fma_f32 v45, v40, s57, -v45
	v_fmac_f32_e32 v45, 0x3377d1cf, v40
	v_fmac_f32_e32 v45, 0x3f317217, v40
	v_cmp_lt_f32_e64 s[0:1], |v40|, s8
	s_nop 1
	v_cndmask_b32_e64 v40, v40, v45, s[0:1]
	v_cndmask_b32_e32 v45, 0, v201, vcc
	v_sub_f32_e32 v40, v40, v45
	v_mul_f32_e32 v45, 0xbfb8aa3b, v59
	v_exp_f32_e32 v45, v45
	s_nop 0
	v_add_f32_e32 v45, 1.0, v45
	v_div_scale_f32 v46, s[0:1], v45, v45, 1.0
	v_rcp_f32_e32 v48, v46
	s_nop 0
	v_fma_f32 v49, -v46, v48, 1.0
	v_fmac_f32_e32 v48, v49, v48
	v_div_scale_f32 v49, vcc, 1.0, v45, 1.0
	v_mul_f32_e32 v56, v49, v48
	v_fma_f32 v57, -v46, v56, v49
	v_fmac_f32_e32 v56, v57, v48
	v_fma_f32 v46, -v46, v56, v49
	v_div_fmas_f32 v46, v46, v48, v56
	v_div_fixup_f32 v45, v46, v45, 1.0
	v_fmac_f32_e32 v41, v55, v45
	v_max_f32_e32 v41, 0xda24260, v41
	v_cmp_gt_f32_e32 vcc, s56, v41
	s_nop 1
	v_cndmask_b32_e64 v45, 0, 32, vcc
	v_ldexp_f32 v41, v41, v45
	v_log_f32_e32 v41, v41
	s_nop 0
	v_mul_f32_e32 v45, 0x3f317217, v41
	v_fma_f32 v45, v41, s57, -v45
	v_fmac_f32_e32 v45, 0x3377d1cf, v41
	v_fmac_f32_e32 v45, 0x3f317217, v41
	v_cmp_lt_f32_e64 s[0:1], |v41|, s8
	s_nop 1
	v_cndmask_b32_e64 v41, v41, v45, s[0:1]
	v_cndmask_b32_e32 v45, 0, v201, vcc
	v_sub_f32_e32 v41, v41, v45
	v_mul_f32_e32 v45, 0xbfb8aa3b, v60
	v_exp_f32_e32 v45, v45
	s_nop 0
	v_add_f32_e32 v45, 1.0, v45
	v_div_scale_f32 v46, s[0:1], v45, v45, 1.0
	v_rcp_f32_e32 v48, v46
	s_nop 0
	v_fma_f32 v49, -v46, v48, 1.0
	v_fmac_f32_e32 v48, v49, v48
	v_div_scale_f32 v49, vcc, 1.0, v45, 1.0
	v_mul_f32_e32 v55, v49, v48
	v_fma_f32 v56, -v46, v55, v49
	v_fmac_f32_e32 v55, v56, v48
	v_fma_f32 v46, -v46, v55, v49
	v_div_fmas_f32 v46, v46, v48, v55
	v_div_fixup_f32 v45, v46, v45, 1.0
	v_fma_f32 v34, v54, v45, v34
	v_max_f32_e32 v34, 0xda24260, v34
	v_cmp_gt_f32_e32 vcc, s56, v34
	s_nop 1
	v_cndmask_b32_e64 v45, 0, 32, vcc
	v_ldexp_f32 v34, v34, v45
	v_log_f32_e32 v34, v34
	s_nop 0
	v_mul_f32_e32 v45, 0x3f317217, v34
	v_fma_f32 v45, v34, s57, -v45
	v_fmac_f32_e32 v45, 0x3377d1cf, v34
	v_fmac_f32_e32 v45, 0x3f317217, v34
	v_cmp_lt_f32_e64 s[0:1], |v34|, s8
	s_nop 1
	v_cndmask_b32_e64 v34, v34, v45, s[0:1]
	v_cndmask_b32_e32 v45, 0, v201, vcc
	v_sub_f32_e32 v34, v34, v45
	v_div_scale_f32 v45, s[0:1], v44, v44, 1.0
	v_rcp_f32_e32 v46, v45
	s_nop 0
	v_fma_f32 v48, -v45, v46, 1.0
	v_fmac_f32_e32 v46, v48, v46
	v_div_scale_f32 v48, vcc, 1.0, v44, 1.0
	v_mul_f32_e32 v49, v48, v46
	v_fma_f32 v54, -v45, v49, v48
; __device__ __forceinline__ float sigmoidf_(float x) { return 1.0f / (1.0f + __expf(-x)); }
; __device__ __forceinline__ void hg_bcum(const Params& p, int l, const u16* Uhg, int t0, int h, float* bc, float* lbs,
;                                         float* tots) {
;     ...
;       const float f = lbv + (1.0f - lbv) * sigmoidf_(z[j]);
;       lf[j] = __logf(fmaxf(f, 1e-30f));
;     }
;     *(float4*)(bc + s * BCS + d0) = make_float4(lf[0], lf[1], lf[2], lf[3]);
;     *(float4*)(bc + s * BCS + d0 + 4) = make_float4(lf[4], lf[5], lf[6], lf[7]);
;   }
;   __syncthreads();
;   {
;     const int d = tid & 127, hf = tid >> 7;
;     float r[32];
;     float run = 0.f;
; #pragma unroll
;     for (int s = 0; s < 32; ++s) { run += bc[(hf * 32 + s) * BCS + d]; r[s] = run; }
;     if (hf == 0) tots[d] = run;
;     __syncthreads();
	v_fmac_f32_e32 v49, v54, v46
	v_fma_f32 v45, -v45, v49, v48
	v_div_fmas_f32 v45, v45, v46, v49
	v_div_fixup_f32 v44, v45, v44, 1.0
	v_fma_f32 v35, v53, v44, v35
	v_max_f32_e32 v35, 0xda24260, v35
	v_cmp_gt_f32_e32 vcc, s56, v35
	s_nop 1
	v_cndmask_b32_e64 v44, 0, 32, vcc
	v_ldexp_f32 v35, v35, v44
	v_log_f32_e32 v35, v35
	s_nop 0
	v_mul_f32_e32 v44, 0x3f317217, v35
	v_fma_f32 v44, v35, s57, -v44
	v_fmac_f32_e32 v44, 0x3377d1cf, v35
	v_fmac_f32_e32 v44, 0x3f317217, v35
	v_cmp_lt_f32_e64 s[0:1], |v35|, s8
	s_nop 1
	v_cndmask_b32_e64 v35, v35, v44, s[0:1]
	v_cndmask_b32_e32 v44, 0, v201, vcc
	v_sub_f32_e32 v35, v35, v44
	v_div_scale_f32 v44, s[0:1], v43, v43, 1.0
	v_rcp_f32_e32 v45, v44
	s_nop 0
	v_fma_f32 v46, -v44, v45, 1.0
	v_fmac_f32_e32 v45, v46, v45
	v_div_scale_f32 v46, vcc, 1.0, v43, 1.0
	v_mul_f32_e32 v48, v46, v45
	v_fma_f32 v49, -v44, v48, v46
	v_fmac_f32_e32 v48, v49, v45
	v_fma_f32 v44, -v44, v48, v46
	v_div_fmas_f32 v44, v44, v45, v48
	v_div_fixup_f32 v43, v44, v43, 1.0
	v_fma_f32 v36, v52, v43, v36
	v_max_f32_e32 v36, 0xda24260, v36
	v_cmp_gt_f32_e32 vcc, s56, v36
	s_nop 1
	v_cndmask_b32_e64 v43, 0, 32, vcc
	v_ldexp_f32 v36, v36, v43
	v_log_f32_e32 v36, v36
	s_nop 0
	v_mul_f32_e32 v43, 0x3f317217, v36
	v_fma_f32 v43, v36, s57, -v43
	v_fmac_f32_e32 v43, 0x3377d1cf, v36
	v_fmac_f32_e32 v43, 0x3f317217, v36
	v_cmp_lt_f32_e64 s[0:1], |v36|, s8
	s_nop 1
	v_cndmask_b32_e64 v36, v36, v43, s[0:1]
	v_cndmask_b32_e32 v43, 0, v201, vcc
	v_sub_f32_e32 v36, v36, v43
	v_div_scale_f32 v43, s[0:1], v42, v42, 1.0
	v_rcp_f32_e32 v44, v43
	s_nop 0
	v_fma_f32 v45, -v43, v44, 1.0
	v_fmac_f32_e32 v44, v45, v44
	v_div_scale_f32 v45, vcc, 1.0, v42, 1.0
	v_mul_f32_e32 v46, v45, v44
	v_fma_f32 v48, -v43, v46, v45
	v_fmac_f32_e32 v46, v48, v44
	v_fma_f32 v43, -v43, v46, v45
	v_div_fmas_f32 v43, v43, v44, v46
	v_div_fixup_f32 v42, v43, v42, 1.0
	v_fmac_f32_e32 v37, v51, v42
	v_max_f32_e32 v37, 0xda24260, v37
	v_cmp_gt_f32_e32 vcc, s56, v37
	s_nop 1
	v_cndmask_b32_e64 v42, 0, 32, vcc
	v_ldexp_f32 v37, v37, v42
	v_log_f32_e32 v37, v37
	s_nop 0
	v_mul_f32_e32 v42, 0x3f317217, v37
	v_fma_f32 v42, v37, s57, -v42
	v_fmac_f32_e32 v42, 0x3377d1cf, v37
	v_fmac_f32_e32 v42, 0x3f317217, v37
	v_cmp_lt_f32_e64 s[0:1], |v37|, s8
	s_nop 1
	v_cndmask_b32_e64 v37, v37, v42, s[0:1]
	v_cndmask_b32_e32 v42, 0, v201, vcc
	v_sub_f32_e32 v37, v37, v42
	ds_write_b128 v47, v[38:41] offset:25344
	ds_write_b128 v47, v[34:37] offset:25360
	v_lshrrev_b32_e32 v34, 2, v50
	v_and_b32_e32 v36, 0x7f, v50
	v_and_b32_e32 v34, 32, v34
	v_mul_u32_u24_e32 v34, 0x210, v34
	v_lshlrev_b32_e32 v35, 2, v36
	v_add3_u32 v34, s69, v34, v35
	s_waitcnt lgkmcnt(0)
	s_barrier
	ds_read2_b32 v[38:39], v34 offset1:132
	v_add_u32_e32 v35, 0x400, v34
	ds_read2_b32 v[40:41], v35 offset0:8 offset1:140
	v_add_u32_e32 v44, 0xc00, v34
	ds_read2_b32 v[46:47], v44 offset0:24 offset1:156
	s_waitcnt lgkmcnt(2)
	v_add_f32_e32 v37, 0, v38
	v_add_f32_e32 v38, v37, v39
	s_waitcnt lgkmcnt(1)
	v_add_f32_e32 v39, v38, v40
	v_add_f32_e32 v40, v39, v41
	v_add_u32_e32 v41, 0x800, v34
	ds_read2_b32 v[42:43], v41 offset0:16 offset1:148
	v_add_u32_e32 v45, 0x1000, v34
	ds_read2_b32 v[48:49], v45 offset0:32 offset1:164
	v_add_u32_e32 v50, 0x1400, v34
	ds_read2_b32 v[52:53], v50 offset0:40 offset1:172
	s_waitcnt lgkmcnt(2)
	v_add_f32_e32 v42, v40, v42
	v_add_f32_e32 v43, v42, v43
	v_add_f32_e32 v46, v43, v46
	v_add_f32_e32 v47, v46, v47
	s_waitcnt lgkmcnt(1)
	v_add_f32_e32 v48, v47, v48
	v_add_f32_e32 v49, v48, v49
	s_waitcnt lgkmcnt(0)
	v_add_f32_e32 v51, v49, v52
	v_add_f32_e32 v52, v51, v53
	v_add_u32_e32 v53, 0x1800, v34
	ds_read2_b32 v[56:57], v53 offset0:48 offset1:180
	v_add_u32_e32 v54, 0x1c00, v34
	ds_read2_b32 v[58:59], v54 offset0:56 offset1:188
	v_add_u32_e32 v62, 0x2400, v34
	ds_read2_b32 v[64:65], v62 offset0:72 offset1:204
	s_waitcnt lgkmcnt(2)
	v_add_f32_e32 v55, v52, v56
	v_add_f32_e32 v56, v55, v57
	s_waitcnt lgkmcnt(1)
	v_add_f32_e32 v57, v56, v58
	v_add_f32_e32 v58, v57, v59
	v_add_u32_e32 v59, 0x2000, v34
	ds_read2_b32 v[60:61], v59 offset0:64 offset1:196
	v_add_u32_e32 v63, 0x2800, v34
	ds_read2_b32 v[66:67], v63 offset0:80 offset1:212
	v_add_u32_e32 v68, 0x2c00, v34
	ds_read2_b32 v[70:71], v68 offset0:88 offset1:220
	s_waitcnt lgkmcnt(2)
	v_add_f32_e32 v60, v58, v60
	v_add_f32_e32 v61, v60, v61
	v_add_f32_e32 v64, v61, v64
	v_add_f32_e32 v65, v64, v65
	s_waitcnt lgkmcnt(1)
	v_add_f32_e32 v66, v65, v66
	v_add_f32_e32 v67, v66, v67
	s_waitcnt lgkmcnt(0)
	v_add_f32_e32 v69, v67, v70
	v_add_f32_e32 v70, v69, v71
	v_add_u32_e32 v71, 0x3000, v34
	ds_read2_b32 v[74:75], v71 offset0:96 offset1:228
	v_add_u32_e32 v72, 0x3400, v34
	ds_read2_b32 v[76:77], v72 offset0:104 offset1:236
	v_add_u32_e32 v80, 0x3c00, v34
	ds_read2_b32 v[82:83], v80 offset0:120 offset1:252
	s_waitcnt lgkmcnt(2)
	v_add_f32_e32 v73, v70, v74
	v_add_f32_e32 v74, v73, v75
	s_waitcnt lgkmcnt(1)
	v_add_f32_e32 v75, v74, v76
	v_add_f32_e32 v76, v75, v77
	v_add_u32_e32 v77, 0x3800, v34
	ds_read2_b32 v[78:79], v77 offset0:112 offset1:244
	v_lshl_add_u32 v84, v36, 2, s71
	s_waitcnt lgkmcnt(0)
	v_add_f32_e32 v78, v76, v78
	v_add_f32_e32 v79, v78, v79
	v_add_f32_e32 v81, v79, v82
	v_add_f32_e32 v82, v81, v83
	s_and_saveexec_b64 s[0:1], s[48:49]
	ds_write_b32 v84, v82
	s_or_b64 exec, exec, s[0:1]
	v_mov_b32_e32 v36, 0
	v_mov_b32_e32 v83, 0
	s_waitcnt lgkmcnt(0)
	s_barrier
; __device__ __forceinline__ void hg_bcum(const Params& p, int l, const u16* Uhg, int t0, int h, float* bc, float* lbs,
;                                         float* tots) {
;     ...
;     const float add = hf ? tots[d] : 0.f;
; #pragma unroll
;     for (int s = 0; s < 32; ++s) bc[(hf * 32 + s) * BCS + d] = r[s] + add;
;   }
;   __syncthreads();
; __device__ __forceinline__ void phase_hg_out(const Params& p, int l, char* smem) {
;     ...
;     {
;       const int d = tid & 127;
;       for (int idx = tid; idx < 64 * 128; idx += 256) {
;         const int s = idx >> 7;
;         VTs[d * 72 + s] = Uhg[(size_t)(t0 + s) * 2048 + 1024 + h * 128 + d];
;       }
;     }
	s_and_saveexec_b64 s[0:1], s[46:47]
	ds_read_b32 v83, v84
	s_or_b64 exec, exec, s[0:1]
	s_waitcnt lgkmcnt(0)
	v_add_f32_e32 v37, v37, v83
	v_add_f32_e32 v38, v38, v83
	ds_write2_b32 v34, v37, v38 offset1:132
	v_add_f32_e32 v34, v39, v83
	v_add_f32_e32 v37, v40, v83
	ds_write2_b32 v35, v34, v37 offset0:8 offset1:140
	v_add_f32_e32 v34, v42, v83
	v_add_f32_e32 v35, v43, v83
	ds_write2_b32 v41, v34, v35 offset0:16 offset1:148
	v_add_f32_e32 v34, v46, v83
	v_add_f32_e32 v35, v47, v83
	ds_write2_b32 v44, v34, v35 offset0:24 offset1:156
	v_add_f32_e32 v34, v48, v83
	v_add_f32_e32 v35, v49, v83
	ds_write2_b32 v45, v34, v35 offset0:32 offset1:164
	v_add_f32_e32 v34, v51, v83
	v_add_f32_e32 v35, v52, v83
	ds_write2_b32 v50, v34, v35 offset0:40 offset1:172
	v_add_f32_e32 v34, v55, v83
	v_add_f32_e32 v35, v56, v83
	ds_write2_b32 v53, v34, v35 offset0:48 offset1:180
	v_add_f32_e32 v34, v57, v83
	v_add_f32_e32 v35, v58, v83
	ds_write2_b32 v54, v34, v35 offset0:56 offset1:188
	v_add_f32_e32 v34, v60, v83
	v_add_f32_e32 v35, v61, v83
	ds_write2_b32 v59, v34, v35 offset0:64 offset1:196
	v_add_f32_e32 v34, v64, v83
	v_add_f32_e32 v35, v65, v83
	ds_write2_b32 v62, v34, v35 offset0:72 offset1:204
	v_add_f32_e32 v34, v66, v83
	v_add_f32_e32 v35, v67, v83
	ds_write2_b32 v63, v34, v35 offset0:80 offset1:212
	v_add_f32_e32 v34, v69, v83
	v_add_f32_e32 v35, v70, v83
	ds_write2_b32 v68, v34, v35 offset0:88 offset1:220
	v_add_f32_e32 v34, v73, v83
	v_add_f32_e32 v35, v74, v83
	ds_write2_b32 v71, v34, v35 offset0:96 offset1:228
	v_add_f32_e32 v34, v75, v83
	v_add_f32_e32 v35, v76, v83
	s_lshl_b32 s0, s20, 7
	ds_write2_b32 v72, v34, v35 offset0:104 offset1:236
	v_add_f32_e32 v34, v78, v83
	v_add_f32_e32 v35, v79, v83
	v_or_b32_e32 v38, s13, v3
	v_or_b32_e32 v40, s13, v2
	v_or_b32_e32 v42, s13, v5
	v_or_b32_e32 v44, s13, v4
	ds_write2_b32 v77, v34, v35 offset0:112 offset1:244
	v_add_f32_e32 v34, v81, v83
	v_add_f32_e32 v35, v82, v83
	s_lshl_b32 s58, s0, 1
	v_ashrrev_i32_e32 v45, 31, v44
	v_ashrrev_i32_e32 v43, 31, v42
	v_ashrrev_i32_e32 v41, 31, v40
	v_ashrrev_i32_e32 v39, 31, v38
	ds_write2_b32 v80, v34, v35 offset0:120 offset1:252
	v_lshl_add_u64 v[34:35], v[136:137], 0, s[58:59]
	v_lshlrev_b64 v[38:39], 12, v[38:39]
	v_lshlrev_b64 v[40:41], 12, v[40:41]
	v_lshlrev_b64 v[42:43], 12, v[42:43]
	v_lshlrev_b64 v[44:45], 12, v[44:45]
	v_lshl_add_u64 v[44:45], v[34:35], 0, v[44:45]
	v_lshl_add_u64 v[42:43], v[34:35], 0, v[42:43]
	v_lshl_add_u64 v[40:41], v[34:35], 0, v[40:41]
	v_lshl_add_u64 v[38:39], v[34:35], 0, v[38:39]
	s_waitcnt lgkmcnt(0)
	s_barrier
	global_load_ushort v98, v[44:45], off offset:2048
	s_nop 0
	global_load_ushort v99, v[42:43], off offset:2048
	s_nop 0
	global_load_ushort v100, v[40:41], off offset:2048
	s_nop 0
	global_load_ushort v101, v[38:39], off offset:2048
	v_or_b32_e32 v44, s13, v8
	v_ashrrev_i32_e32 v45, 31, v44
	v_lshlrev_b64 v[44:45], 12, v[44:45]
	v_lshl_add_u64 v[44:45], v[34:35], 0, v[44:45]
	v_mov_b32_e32 v96, 0
	v_mov_b32_e32 v97, 0
	v_mov_b32_e32 v94, 0
	v_mov_b32_e32 v95, 0
	v_or_b32_e32 v38, s13, v7
	v_or_b32_e32 v40, s13, v6
	v_or_b32_e32 v42, s13, v9
	v_ashrrev_i32_e32 v43, 31, v42
	v_ashrrev_i32_e32 v41, 31, v40
	v_ashrrev_i32_e32 v39, 31, v38
	v_lshlrev_b64 v[38:39], 12, v[38:39]
	v_lshlrev_b64 v[40:41], 12, v[40:41]
	v_lshlrev_b64 v[42:43], 12, v[42:43]
	v_lshl_add_u64 v[42:43], v[34:35], 0, v[42:43]
	v_lshl_add_u64 v[40:41], v[34:35], 0, v[40:41]
	v_lshl_add_u64 v[38:39], v[34:35], 0, v[38:39]
	global_load_ushort v102, v[44:45], off offset:2048
	s_nop 0
	global_load_ushort v103, v[42:43], off offset:2048
	s_nop 0
	global_load_ushort v104, v[40:41], off offset:2048
	s_nop 0
	global_load_ushort v105, v[38:39], off offset:2048
	v_or_b32_e32 v44, s13, v12
	v_ashrrev_i32_e32 v45, 31, v44
	v_lshlrev_b64 v[44:45], 12, v[44:45]
	v_lshl_add_u64 v[44:45], v[34:35], 0, v[44:45]
	v_or_b32_e32 v38, s13, v11
	v_or_b32_e32 v40, s13, v10
	v_or_b32_e32 v42, s13, v13
	v_ashrrev_i32_e32 v43, 31, v42
	v_ashrrev_i32_e32 v41, 31, v40
	v_ashrrev_i32_e32 v39, 31, v38
	v_lshlrev_b64 v[38:39], 12, v[38:39]
	v_lshlrev_b64 v[40:41], 12, v[40:41]
	v_lshlrev_b64 v[42:43], 12, v[42:43]
	v_lshl_add_u64 v[42:43], v[34:35], 0, v[42:43]
	v_lshl_add_u64 v[40:41], v[34:35], 0, v[40:41]
	v_lshl_add_u64 v[38:39], v[34:35], 0, v[38:39]
	global_load_ushort v106, v[44:45], off offset:2048
	s_nop 0
	global_load_ushort v107, v[42:43], off offset:2048
	s_nop 0
	global_load_ushort v108, v[40:41], off offset:2048
	s_nop 0
	global_load_ushort v109, v[38:39], off offset:2048
	v_or_b32_e32 v44, s13, v16
	v_ashrrev_i32_e32 v45, 31, v44
	v_lshlrev_b64 v[44:45], 12, v[44:45]
	v_lshl_add_u64 v[44:45], v[34:35], 0, v[44:45]
	v_or_b32_e32 v38, s13, v15
	v_or_b32_e32 v40, s13, v14
	v_or_b32_e32 v42, s13, v17
	v_ashrrev_i32_e32 v43, 31, v42
	v_ashrrev_i32_e32 v41, 31, v40
	v_ashrrev_i32_e32 v39, 31, v38
	v_lshlrev_b64 v[38:39], 12, v[38:39]
	v_lshlrev_b64 v[40:41], 12, v[40:41]
	v_lshlrev_b64 v[42:43], 12, v[42:43]
	v_lshl_add_u64 v[42:43], v[34:35], 0, v[42:43]
	v_lshl_add_u64 v[40:41], v[34:35], 0, v[40:41]
; __device__ __forceinline__ void phase_hg_out(const Params& p, int l, char* smem) {
;     ...
;     {
;       const int d = tid & 127;
;       for (int idx = tid; idx < 64 * 128; idx += 256) {
;         const int s = idx >> 7;
;         VTs[d * 72 + s] = Uhg[(size_t)(t0 + s) * 2048 + 1024 + h * 128 + d];
;       }
;     }
;     __syncthreads();
;     const int tt = wave * 16 + c16;
;     const bool hi = (wave >= 2);
;     bf16x8 Qt[4], Qh[4];
;     float rr8[4][8];
; #pragma unroll
;     for (int ks = 0; ks < 4; ++ks) {
;       const int d0 = ks * 32 + q * 8;
;       if (hi) load8f(bc + 31 * BCS + d0, rr8[ks]);
	v_lshl_add_u64 v[38:39], v[34:35], 0, v[38:39]
	global_load_ushort v110, v[44:45], off offset:2048
	s_nop 0
	global_load_ushort v111, v[42:43], off offset:2048
	s_nop 0
	global_load_ushort v112, v[40:41], off offset:2048
	s_nop 0
	global_load_ushort v113, v[38:39], off offset:2048
	v_or_b32_e32 v38, s13, v19
	v_or_b32_e32 v40, s13, v18
	v_or_b32_e32 v42, s13, v21
	v_or_b32_e32 v44, s13, v20
	v_ashrrev_i32_e32 v45, 31, v44
	v_ashrrev_i32_e32 v43, 31, v42
	v_ashrrev_i32_e32 v41, 31, v40
	v_ashrrev_i32_e32 v39, 31, v38
	v_lshlrev_b64 v[38:39], 12, v[38:39]
	v_lshlrev_b64 v[40:41], 12, v[40:41]
	v_lshlrev_b64 v[42:43], 12, v[42:43]
	v_lshlrev_b64 v[44:45], 12, v[44:45]
	v_lshl_add_u64 v[44:45], v[34:35], 0, v[44:45]
	v_lshl_add_u64 v[42:43], v[34:35], 0, v[42:43]
	v_lshl_add_u64 v[40:41], v[34:35], 0, v[40:41]
	v_lshl_add_u64 v[38:39], v[34:35], 0, v[38:39]
	global_load_ushort v114, v[44:45], off offset:2048
	s_nop 0
	global_load_ushort v115, v[42:43], off offset:2048
	s_nop 0
	global_load_ushort v116, v[40:41], off offset:2048
	s_nop 0
	global_load_ushort v117, v[38:39], off offset:2048
	v_or_b32_e32 v38, s13, v23
	v_or_b32_e32 v40, s13, v22
	v_or_b32_e32 v42, s13, v25
	v_or_b32_e32 v44, s13, v24
	v_ashrrev_i32_e32 v45, 31, v44
	v_ashrrev_i32_e32 v43, 31, v42
	v_ashrrev_i32_e32 v41, 31, v40
	v_ashrrev_i32_e32 v39, 31, v38
	v_lshlrev_b64 v[38:39], 12, v[38:39]
	v_lshlrev_b64 v[40:41], 12, v[40:41]
	v_lshlrev_b64 v[42:43], 12, v[42:43]
	v_lshlrev_b64 v[44:45], 12, v[44:45]
	v_lshl_add_u64 v[44:45], v[34:35], 0, v[44:45]
	v_lshl_add_u64 v[42:43], v[34:35], 0, v[42:43]
	v_lshl_add_u64 v[40:41], v[34:35], 0, v[40:41]
	v_lshl_add_u64 v[38:39], v[34:35], 0, v[38:39]
	global_load_ushort v118, v[44:45], off offset:2048
	s_nop 0
	global_load_ushort v119, v[42:43], off offset:2048
	s_nop 0
	global_load_ushort v120, v[40:41], off offset:2048
	s_nop 0
	global_load_ushort v121, v[38:39], off offset:2048
	v_or_b32_e32 v38, s13, v27
	v_or_b32_e32 v40, s13, v26
	v_or_b32_e32 v42, s13, v29
	v_or_b32_e32 v44, s13, v28
	v_ashrrev_i32_e32 v45, 31, v44
	v_ashrrev_i32_e32 v43, 31, v42
	v_ashrrev_i32_e32 v41, 31, v40
	v_ashrrev_i32_e32 v39, 31, v38
	v_lshlrev_b64 v[38:39], 12, v[38:39]
	v_lshlrev_b64 v[40:41], 12, v[40:41]
	v_lshlrev_b64 v[42:43], 12, v[42:43]
	v_lshlrev_b64 v[44:45], 12, v[44:45]
	v_lshl_add_u64 v[44:45], v[34:35], 0, v[44:45]
	v_lshl_add_u64 v[42:43], v[34:35], 0, v[42:43]
	v_lshl_add_u64 v[40:41], v[34:35], 0, v[40:41]
	v_lshl_add_u64 v[38:39], v[34:35], 0, v[38:39]
	global_load_ushort v122, v[44:45], off offset:2048
	s_nop 0
	global_load_ushort v123, v[42:43], off offset:2048
	s_nop 0
	global_load_ushort v124, v[40:41], off offset:2048
	s_nop 0
	global_load_ushort v125, v[38:39], off offset:2048
	v_or_b32_e32 v38, s13, v31
	v_or_b32_e32 v40, s13, v30
	v_or_b32_e32 v42, s13, v33
	v_or_b32_e32 v44, s13, v32
	v_ashrrev_i32_e32 v45, 31, v44
	v_ashrrev_i32_e32 v43, 31, v42
	v_ashrrev_i32_e32 v41, 31, v40
	v_ashrrev_i32_e32 v39, 31, v38
	v_lshlrev_b64 v[38:39], 12, v[38:39]
	v_lshlrev_b64 v[40:41], 12, v[40:41]
	v_lshlrev_b64 v[42:43], 12, v[42:43]
	v_lshlrev_b64 v[44:45], 12, v[44:45]
	v_lshl_add_u64 v[44:45], v[34:35], 0, v[44:45]
	v_lshl_add_u64 v[42:43], v[34:35], 0, v[42:43]
	v_lshl_add_u64 v[40:41], v[34:35], 0, v[40:41]
	v_lshl_add_u64 v[34:35], v[34:35], 0, v[38:39]
	global_load_ushort v126, v[44:45], off offset:2048
	global_load_ushort v127, v[42:43], off offset:2048
	global_load_ushort v128, v[40:41], off offset:2048
	s_nop 0
	global_load_ushort v129, v[34:35], off offset:2048
	s_waitcnt vmcnt(0)
	ds_write_b16 v222, v98 offset:34304
	ds_write_b16 v223, v99 offset:34304
	ds_write_b16 v224, v100 offset:34304
	ds_write_b16 v225, v101 offset:34304
	ds_write_b16 v226, v102 offset:34304
	ds_write_b16 v227, v103 offset:34304
	ds_write_b16 v228, v104 offset:34304
	ds_write_b16 v229, v105 offset:34304
	ds_write_b16 v230, v106 offset:34304
	ds_write_b16 v231, v107 offset:34304
	ds_write_b16 v232, v108 offset:34304
	ds_write_b16 v233, v109 offset:34304
	ds_write_b16 v234, v110 offset:34304
	ds_write_b16 v235, v111 offset:34304
	ds_write_b16 v236, v112 offset:34304
	ds_write_b16 v237, v113 offset:34304
	ds_write_b16 v238, v114 offset:34304
	ds_write_b16 v239, v115 offset:34304
	ds_write_b16 v240, v116 offset:34304
	ds_write_b16 v241, v117 offset:34304
	ds_write_b16 v242, v118 offset:34304
	ds_write_b16 v243, v119 offset:34304
	ds_write_b16 v244, v120 offset:34304
	ds_write_b16 v245, v121 offset:34304
	ds_write_b16 v246, v122 offset:34304
	ds_write_b16 v247, v123 offset:34304
	ds_write_b16 v248, v124 offset:34304
	ds_write_b16 v249, v125 offset:34304
	ds_write_b16 v250, v126 offset:34304
	ds_write_b16 v251, v127 offset:34304
	ds_write_b16 v199, v128 offset:34304
	ds_write_b16 v200, v129 offset:34304
	v_mov_b32_e32 v37, 0
	v_mov_b32_e32 v34, 0
	v_mov_b32_e32 v35, 0
	s_waitcnt lgkmcnt(0)
	s_barrier
	s_and_saveexec_b64 s[0:1], s[50:51]
	s_cbranch_execz .LBB0_45
	ds_read_b128 v[94:97], v204 offset:16368
	ds_read_b128 v[34:37], v204 offset:16384

; __device__ __forceinline__ float sigmoidf_(float x) { return 1.0f / (1.0f + __expf(-x)); }
; __device__ __forceinline__ void hg_bcum(const Params& p, int l, const u16* Uhg, int t0, int h, float* bc, float* lbs,
;                                         float* tots) {
;     ...
;   __syncthreads();
; #pragma unroll
;   for (int k = 0; k < 4; ++k) {
;     const int s = (tid >> 4) + 16 * k, d0 = (tid & 15) * 8;
;     float z[8];
;     unpack8(*(const uint4*)(Uhg + (size_t)(t0 + s) * 2048 + 512 + h * 128 + d0), z);
;     float lf[8];
; #pragma unroll
;     for (int j = 0; j < 8; ++j) {
;       const float lbv = lbs[d0 + j];
;       const float f = lbv + (1.0f - lbv) * sigmoidf_(z[j]);
;       lf[j] = __logf(fmaxf(f, 1e-30f));
;     }
;     *(float4*)(bc + s * BCS + d0) = make_float4(lf[0], lf[1], lf[2], lf[3]);
;     *(float4*)(bc + s * BCS + d0 + 4) = make_float4(lf[4], lf[5], lf[6], lf[7]);
.LBB0_381:
	s_or_b64 exec, exec, s[0:1]
	s_lshl_b32 s0, s48, 4
	s_lshl_b32 s1, s48, 6
	s_and_b32 s0, s0, 0xffffe000
	s_and_b32 s1, s1, 0x1fc0
	s_or_b32 s0, s0, s1
	v_lshrrev_b32_e32 v35, 4, v2
	v_or_b32_e32 v14, s0, v35
	v_lshlrev_b32_e32 v2, 3, v18
	v_ashrrev_i32_e32 v15, 31, v14
	v_readlane_b32 s22, v252, 46
	v_and_b32_e32 v4, 0x78, v2
	v_lshlrev_b64 v[2:3], 12, v[14:15]
	v_readlane_b32 s23, v252, 47
	s_lshl_b32 s58, s10, 8
	v_lshlrev_b32_e32 v16, 1, v4
	v_lshl_add_u64 v[2:3], s[22:23], 0, v[2:3]
	v_lshl_add_u64 v[2:3], v[2:3], 0, s[58:59]
	v_mov_b32_e32 v17, v1
	v_lshl_add_u64 v[2:3], v[2:3], 0, v[16:17]
	s_waitcnt lgkmcnt(0)
	s_barrier
	v_lshl_add_u32 v37, v4, 2, s69
	s_mov_b32 s98, 0x10000
	s_mov_b32 s99, 0
	v_lshl_add_u64 v[170:171], v[2:3], 0, s[98:99]
	global_load_dwordx4 v[2:5], v[2:3], off offset:1024
	global_load_dwordx4 v[158:161], v[170:171], off offset:1024
	v_lshl_add_u64 v[170:171], v[170:171], 0, s[98:99]
	global_load_dwordx4 v[162:165], v[170:171], off offset:1024
	v_lshl_add_u64 v[170:171], v[170:171], 0, s[98:99]
	global_load_dwordx4 v[166:169], v[170:171], off offset:1024
	v_and_b32_e32 v80, 0x7f, v18
	s_waitcnt vmcnt(3)
	v_lshlrev_b32_e32 v10, 16, v2
	v_mul_f32_e32 v10, 0xbfb8aa3b, v10
	v_exp_f32_e32 v10, v10
	v_and_b32_e32 v11, 0xffff0000, v2
	v_lshlrev_b32_e32 v12, 16, v3
	v_and_b32_e32 v13, 0xffff0000, v3
	v_add_f32_e32 v10, 1.0, v10
	v_div_scale_f32 v20, s[0:1], v10, v10, 1.0
	v_rcp_f32_e32 v21, v20
	v_lshlrev_b32_e32 v15, 16, v4
	v_and_b32_e32 v19, 0xffff0000, v4
	v_lshlrev_b32_e32 v39, 16, v5
	v_fma_f32 v22, -v20, v21, 1.0
	v_fmac_f32_e32 v21, v22, v21
	v_div_scale_f32 v22, vcc, 1.0, v10, 1.0
	v_mul_f32_e32 v23, v22, v21
	v_and_b32_e32 v41, 0xffff0000, v5
	ds_read_b128 v[6:9], v37 offset:33792
	ds_read_b128 v[2:5], v37 offset:33808
	v_fma_f32 v24, -v20, v23, v22
	v_fmac_f32_e32 v23, v24, v21
	v_fma_f32 v20, -v20, v23, v22
	v_div_fmas_f32 v20, v20, v21, v23
	s_waitcnt lgkmcnt(1)
	v_sub_f32_e32 v33, 1.0, v6
	v_div_fixup_f32 v10, v20, v10, 1.0
	v_fma_f32 v10, v33, v10, v6
	v_max_f32_e32 v10, 0xda24260, v10
	v_cmp_gt_f32_e32 vcc, s56, v10
	v_mul_f32_e32 v11, 0xbfb8aa3b, v11
	v_exp_f32_e32 v11, v11
	v_cndmask_b32_e64 v20, 0, 32, vcc
	v_ldexp_f32 v10, v10, v20
	v_log_f32_e32 v10, v10
	v_add_f32_e32 v11, 1.0, v11
	v_sub_f32_e32 v25, 1.0, v7
	v_mul_f32_e32 v12, 0xbfb8aa3b, v12
	v_mul_f32_e32 v20, 0x3f317217, v10
	v_fma_f32 v20, v10, s57, -v20
	v_fmac_f32_e32 v20, 0x3377d1cf, v10
	v_fmac_f32_e32 v20, 0x3f317217, v10
	v_cmp_lt_f32_e64 s[0:1], |v10|, s8
	v_exp_f32_e32 v12, v12
	v_mul_f32_e32 v13, 0xbfb8aa3b, v13
	v_cndmask_b32_e64 v10, v10, v20, s[0:1]
	v_cndmask_b32_e32 v20, 0, v201, vcc
	v_sub_f32_e32 v10, v10, v20
	v_div_scale_f32 v20, s[0:1], v11, v11, 1.0
	v_rcp_f32_e32 v21, v20
	v_add_f32_e32 v12, 1.0, v12
	v_exp_f32_e32 v13, v13
	v_mul_f32_e32 v15, 0xbfb8aa3b, v15
	v_fma_f32 v22, -v20, v21, 1.0
	v_fmac_f32_e32 v21, v22, v21
	v_div_scale_f32 v22, vcc, 1.0, v11, 1.0
	v_mul_f32_e32 v23, v22, v21
	v_fma_f32 v24, -v20, v23, v22
	v_fmac_f32_e32 v23, v24, v21
	v_fma_f32 v20, -v20, v23, v22
	v_div_fmas_f32 v20, v20, v21, v23
	v_div_fixup_f32 v11, v20, v11, 1.0
	v_fma_f32 v11, v11, v25, v7
	v_max_f32_e32 v11, 0xda24260, v11
	v_cmp_gt_f32_e32 vcc, s56, v11
	v_sub_f32_e32 v24, 1.0, v8
	v_add_f32_e32 v13, 1.0, v13
	v_cndmask_b32_e64 v20, 0, 32, vcc
	v_ldexp_f32 v11, v11, v20
	v_log_f32_e32 v11, v11
	v_exp_f32_e32 v15, v15
	v_mul_f32_e32 v20, 0x3f317217, v11
	v_fma_f32 v20, v11, s57, -v20
	v_fmac_f32_e32 v20, 0x3377d1cf, v11
	v_fmac_f32_e32 v20, 0x3f317217, v11
	v_cmp_lt_f32_e64 s[0:1], |v11|, s8
	v_add_f32_e32 v15, 1.0, v15
	s_nop 0
	v_cndmask_b32_e64 v11, v11, v20, s[0:1]
	v_cndmask_b32_e32 v20, 0, v201, vcc
	v_sub_f32_e32 v11, v11, v20
	v_div_scale_f32 v20, s[0:1], v12, v12, 1.0
	v_rcp_f32_e32 v21, v20
	s_nop 0
	v_fma_f32 v22, -v20, v21, 1.0
	v_fmac_f32_e32 v21, v22, v21
	v_div_scale_f32 v22, vcc, 1.0, v12, 1.0
	v_mul_f32_e32 v23, v22, v21
	v_fma_f32 v43, -v20, v23, v22
	v_fmac_f32_e32 v23, v43, v21
	v_fma_f32 v20, -v20, v23, v22
	v_div_fmas_f32 v20, v20, v21, v23
	v_div_fixup_f32 v12, v20, v12, 1.0
	v_fma_f32 v12, v12, v24, v8
	v_max_f32_e32 v12, 0xda24260, v12
	v_cmp_gt_f32_e32 vcc, s56, v12
	v_sub_f32_e32 v23, 1.0, v9
	s_nop 0
	v_cndmask_b32_e64 v20, 0, 32, vcc
	v_ldexp_f32 v12, v12, v20
	v_log_f32_e32 v12, v12
	s_nop 0
	v_mul_f32_e32 v20, 0x3f317217, v12
	v_fma_f32 v20, v12, s57, -v20
	v_fmac_f32_e32 v20, 0x3377d1cf, v12
	v_fmac_f32_e32 v20, 0x3f317217, v12
	v_cmp_lt_f32_e64 s[0:1], |v12|, s8
	s_nop 1
	v_cndmask_b32_e64 v12, v12, v20, s[0:1]
	v_cndmask_b32_e32 v20, 0, v201, vcc
	v_sub_f32_e32 v12, v12, v20
	v_div_scale_f32 v20, s[0:1], v13, v13, 1.0
	v_rcp_f32_e32 v21, v20
	s_nop 0
	v_fma_f32 v22, -v20, v21, 1.0
	v_fmac_f32_e32 v21, v22, v21
	v_div_scale_f32 v22, vcc, 1.0, v13, 1.0
	v_mul_f32_e32 v43, v22, v21
	v_fma_f32 v45, -v20, v43, v22
	v_fmac_f32_e32 v43, v45, v21
	v_fma_f32 v20, -v20, v43, v22
	v_div_fmas_f32 v20, v20, v21, v43
	v_div_fixup_f32 v13, v20, v13, 1.0
	v_fma_f32 v13, v13, v23, v9
	v_max_f32_e32 v13, 0xda24260, v13
	v_cmp_gt_f32_e32 vcc, s56, v13
	s_waitcnt lgkmcnt(0)
; __device__ __forceinline__ float sigmoidf_(float x) { return 1.0f / (1.0f + __expf(-x)); }
; __device__ __forceinline__ void hg_bcum(const Params& p, int l, const u16* Uhg, int t0, int h, float* bc, float* lbs,
;                                         float* tots) {
;     ...
;   for (int k = 0; k < 4; ++k) {
;     const int s = (tid >> 4) + 16 * k, d0 = (tid & 15) * 8;
;     float z[8];
;     unpack8(*(const uint4*)(Uhg + (size_t)(t0 + s) * 2048 + 512 + h * 128 + d0), z);
;     float lf[8];
; #pragma unroll
;     for (int j = 0; j < 8; ++j) {
;       const float lbv = lbs[d0 + j];
;       const float f = lbv + (1.0f - lbv) * sigmoidf_(z[j]);
;       lf[j] = __logf(fmaxf(f, 1e-30f));
;     }
;     *(float4*)(bc + s * BCS + d0) = make_float4(lf[0], lf[1], lf[2], lf[3]);
;     *(float4*)(bc + s * BCS + d0 + 4) = make_float4(lf[4], lf[5], lf[6], lf[7]);
	v_sub_f32_e32 v22, 1.0, v2
	v_cndmask_b32_e64 v20, 0, 32, vcc
	v_ldexp_f32 v13, v13, v20
	v_log_f32_e32 v13, v13
	s_nop 0
	v_mul_f32_e32 v20, 0x3f317217, v13
	v_fma_f32 v20, v13, s57, -v20
	v_fmac_f32_e32 v20, 0x3377d1cf, v13
	v_fmac_f32_e32 v20, 0x3f317217, v13
	v_cmp_lt_f32_e64 s[0:1], |v13|, s8
	s_nop 1
	v_cndmask_b32_e64 v13, v13, v20, s[0:1]
	v_cndmask_b32_e32 v20, 0, v201, vcc
	v_sub_f32_e32 v13, v13, v20
	v_div_scale_f32 v20, s[0:1], v15, v15, 1.0
	v_rcp_f32_e32 v21, v20
	s_nop 0
	v_fma_f32 v43, -v20, v21, 1.0
	v_fmac_f32_e32 v21, v43, v21
	v_div_scale_f32 v43, vcc, 1.0, v15, 1.0
	v_mul_f32_e32 v45, v43, v21
	v_fma_f32 v62, -v20, v45, v43
	v_fmac_f32_e32 v45, v62, v21
	v_fma_f32 v20, -v20, v45, v43
	v_div_fmas_f32 v20, v20, v21, v45
	v_div_fixup_f32 v15, v20, v15, 1.0
	v_fma_f32 v15, v15, v22, v2
	v_max_f32_e32 v15, 0xda24260, v15
	v_cmp_gt_f32_e32 vcc, s56, v15
	v_sub_f32_e32 v21, 1.0, v3
	s_nop 0
	v_cndmask_b32_e64 v20, 0, 32, vcc
	v_ldexp_f32 v15, v15, v20
	v_log_f32_e32 v15, v15
	s_nop 0
	v_mul_f32_e32 v20, 0x3f317217, v15
	v_fma_f32 v20, v15, s57, -v20
	v_fmac_f32_e32 v20, 0x3377d1cf, v15
	v_fmac_f32_e32 v20, 0x3f317217, v15
	v_cmp_lt_f32_e64 s[0:1], |v15|, s8
	s_nop 1
	v_cndmask_b32_e64 v15, v15, v20, s[0:1]
	v_cndmask_b32_e32 v20, 0, v201, vcc
	v_sub_f32_e32 v62, v15, v20
	v_mul_f32_e32 v15, 0xbfb8aa3b, v19
	v_exp_f32_e32 v15, v15
	s_nop 0
	v_add_f32_e32 v15, 1.0, v15
	v_div_scale_f32 v19, s[0:1], v15, v15, 1.0
	v_rcp_f32_e32 v20, v19
	s_nop 0
	v_fma_f32 v43, -v19, v20, 1.0
	v_fmac_f32_e32 v20, v43, v20
	v_div_scale_f32 v43, vcc, 1.0, v15, 1.0
	v_mul_f32_e32 v45, v43, v20
	v_fma_f32 v63, -v19, v45, v43
	v_fmac_f32_e32 v45, v63, v20
	v_fma_f32 v19, -v19, v45, v43
	v_div_fmas_f32 v19, v19, v20, v45
	v_div_fixup_f32 v15, v19, v15, 1.0
	v_fma_f32 v15, v15, v21, v3
	v_max_f32_e32 v15, 0xda24260, v15
	v_cmp_gt_f32_e32 vcc, s56, v15
	v_sub_f32_e32 v20, 1.0, v4
	s_nop 0
	v_cndmask_b32_e64 v19, 0, 32, vcc
	v_ldexp_f32 v15, v15, v19
	v_log_f32_e32 v15, v15
	s_nop 0
	v_mul_f32_e32 v19, 0x3f317217, v15
	v_fma_f32 v19, v15, s57, -v19
	v_fmac_f32_e32 v19, 0x3377d1cf, v15
	v_fmac_f32_e32 v19, 0x3f317217, v15
	v_cmp_lt_f32_e64 s[0:1], |v15|, s8
	s_nop 1
	v_cndmask_b32_e64 v15, v15, v19, s[0:1]
	v_cndmask_b32_e32 v19, 0, v201, vcc
	v_sub_f32_e32 v63, v15, v19
	v_mul_f32_e32 v15, 0xbfb8aa3b, v39
	v_exp_f32_e32 v15, v15
	s_nop 0
	v_add_f32_e32 v15, 1.0, v15
	v_div_scale_f32 v19, s[0:1], v15, v15, 1.0
	v_rcp_f32_e32 v39, v19
	s_nop 0
	v_fma_f32 v43, -v19, v39, 1.0
	v_fmac_f32_e32 v39, v43, v39
	v_div_scale_f32 v43, vcc, 1.0, v15, 1.0
	v_mul_f32_e32 v45, v43, v39
	v_fma_f32 v64, -v19, v45, v43
	v_fmac_f32_e32 v45, v64, v39
	v_fma_f32 v19, -v19, v45, v43
	v_div_fmas_f32 v19, v19, v39, v45
	v_div_fixup_f32 v15, v19, v15, 1.0
	v_fma_f32 v15, v15, v20, v4
	v_max_f32_e32 v15, 0xda24260, v15
	v_cmp_gt_f32_e32 vcc, s56, v15
	s_nop 1
	v_cndmask_b32_e64 v19, 0, 32, vcc
	v_ldexp_f32 v15, v15, v19
	v_log_f32_e32 v15, v15
	s_nop 0
	v_mul_f32_e32 v19, 0x3f317217, v15
	v_fma_f32 v19, v15, s57, -v19
	v_fmac_f32_e32 v19, 0x3377d1cf, v15
	v_fmac_f32_e32 v19, 0x3f317217, v15
	v_cmp_lt_f32_e64 s[0:1], |v15|, s8
	s_nop 1
	v_cndmask_b32_e64 v15, v15, v19, s[0:1]
	v_cndmask_b32_e32 v19, 0, v201, vcc
	v_sub_f32_e32 v64, v15, v19
	v_mul_f32_e32 v15, 0xbfb8aa3b, v41
	v_exp_f32_e32 v15, v15
	v_sub_f32_e32 v19, 1.0, v5
	v_add_f32_e32 v15, 1.0, v15
	v_div_scale_f32 v39, s[0:1], v15, v15, 1.0
	v_rcp_f32_e32 v41, v39
	s_nop 0
	v_fma_f32 v43, -v39, v41, 1.0
	v_fmac_f32_e32 v41, v43, v41
	v_div_scale_f32 v43, vcc, 1.0, v15, 1.0
	v_mul_f32_e32 v45, v43, v41
	v_fma_f32 v65, -v39, v45, v43
	v_fmac_f32_e32 v45, v65, v41
	v_fma_f32 v39, -v39, v45, v43
	v_div_fmas_f32 v39, v39, v41, v45
	v_div_fixup_f32 v15, v39, v15, 1.0
	v_fma_f32 v15, v15, v19, v5
	v_max_f32_e32 v15, 0xda24260, v15
	v_cmp_gt_f32_e32 vcc, s56, v15
	s_nop 1
	v_cndmask_b32_e64 v39, 0, 32, vcc
	v_ldexp_f32 v15, v15, v39
	v_log_f32_e32 v15, v15
	s_nop 0
	v_mul_f32_e32 v39, 0x3f317217, v15
	v_fma_f32 v39, v15, s57, -v39
	v_fmac_f32_e32 v39, 0x3377d1cf, v15
	v_fmac_f32_e32 v39, 0x3f317217, v15
	v_cmp_lt_f32_e64 s[0:1], |v15|, s8
	s_nop 1
	v_cndmask_b32_e64 v15, v15, v39, s[0:1]
	v_cndmask_b32_e32 v39, 0, v201, vcc
	v_sub_f32_e32 v65, v15, v39
	v_mad_u32_u24 v15, v35, s2, v37
	ds_write_b128 v15, v[10:13]
	ds_write_b128 v15, v[62:65] offset:16
	v_or_b32_e32 v10, 16, v14
	v_ashrrev_i32_e32 v11, 31, v10
	v_lshlrev_b64 v[10:11], 12, v[10:11]
	v_lshl_add_u64 v[10:11], s[22:23], 0, v[10:11]
	v_lshl_add_u64 v[10:11], v[10:11], 0, s[58:59]
	v_lshl_add_u64 v[10:11], v[10:11], 0, v[16:17]
	s_waitcnt vmcnt(2)
; __device__ __forceinline__ float sigmoidf_(float x) { return 1.0f / (1.0f + __expf(-x)); }
; __device__ __forceinline__ void hg_bcum(const Params& p, int l, const u16* Uhg, int t0, int h, float* bc, float* lbs,
;                                         float* tots) {
;     ...
;   for (int k = 0; k < 4; ++k) {
;     const int s = (tid >> 4) + 16 * k, d0 = (tid & 15) * 8;
;     float z[8];
;     unpack8(*(const uint4*)(Uhg + (size_t)(t0 + s) * 2048 + 512 + h * 128 + d0), z);
;     float lf[8];
; #pragma unroll
;     for (int j = 0; j < 8; ++j) {
;       const float lbv = lbs[d0 + j];
;       const float f = lbv + (1.0f - lbv) * sigmoidf_(z[j]);
;       lf[j] = __logf(fmaxf(f, 1e-30f));
;     }
;     *(float4*)(bc + s * BCS + d0) = make_float4(lf[0], lf[1], lf[2], lf[3]);
;     *(float4*)(bc + s * BCS + d0 + 4) = make_float4(lf[4], lf[5], lf[6], lf[7]);
	v_mov_b64_e32 v[10:11], v[158:159]
	v_mov_b64_e32 v[12:13], v[160:161]
	v_lshlrev_b32_e32 v39, 16, v10
	v_and_b32_e32 v41, 0xffff0000, v10
	v_mul_f32_e32 v10, 0xbfb8aa3b, v39
	v_exp_f32_e32 v10, v10
	v_lshlrev_b32_e32 v43, 16, v11
	v_and_b32_e32 v45, 0xffff0000, v11
	v_lshlrev_b32_e32 v62, 16, v12
	v_add_f32_e32 v10, 1.0, v10
	v_div_scale_f32 v11, s[0:1], v10, v10, 1.0
	v_and_b32_e32 v63, 0xffff0000, v12
	v_rcp_f32_e32 v12, v11
	v_lshlrev_b32_e32 v37, 16, v13
	v_and_b32_e32 v35, 0xffff0000, v13
	v_mul_f32_e32 v37, 0xbfb8aa3b, v37
	v_fma_f32 v13, -v11, v12, 1.0
	v_fmac_f32_e32 v12, v13, v12
	v_div_scale_f32 v13, vcc, 1.0, v10, 1.0
	v_mul_f32_e32 v39, v13, v12
	v_fma_f32 v64, -v11, v39, v13
	v_fmac_f32_e32 v39, v64, v12
	v_fma_f32 v11, -v11, v39, v13
	v_div_fmas_f32 v11, v11, v12, v39
	v_div_fixup_f32 v10, v11, v10, 1.0
	v_fma_f32 v10, v33, v10, v6
	v_max_f32_e32 v10, 0xda24260, v10
	v_cmp_gt_f32_e32 vcc, s56, v10
	v_exp_f32_e32 v37, v37
	v_mul_f32_e32 v35, 0xbfb8aa3b, v35
	v_cndmask_b32_e64 v11, 0, 32, vcc
	v_ldexp_f32 v10, v10, v11
	v_log_f32_e32 v10, v10
	v_add_f32_e32 v37, 1.0, v37
	v_exp_f32_e32 v35, v35
	v_mul_f32_e32 v11, 0x3f317217, v10
	v_fma_f32 v11, v10, s57, -v11
	v_fmac_f32_e32 v11, 0x3377d1cf, v10
	v_fmac_f32_e32 v11, 0x3f317217, v10
	v_cmp_lt_f32_e64 s[0:1], |v10|, s8
	v_add_f32_e32 v35, 1.0, v35
	s_nop 0
	v_cndmask_b32_e64 v10, v10, v11, s[0:1]
	v_cndmask_b32_e32 v11, 0, v201, vcc
	v_sub_f32_e32 v10, v10, v11
	v_mul_f32_e32 v11, 0xbfb8aa3b, v41
	v_exp_f32_e32 v11, v11
	s_nop 0
	v_add_f32_e32 v11, 1.0, v11
	v_div_scale_f32 v12, s[0:1], v11, v11, 1.0
	v_rcp_f32_e32 v13, v12
	s_nop 0
	v_fma_f32 v39, -v12, v13, 1.0
	v_fmac_f32_e32 v13, v39, v13
	v_div_scale_f32 v39, vcc, 1.0, v11, 1.0
	v_mul_f32_e32 v41, v39, v13
	v_fma_f32 v64, -v12, v41, v39
	v_fmac_f32_e32 v41, v64, v13
	v_fma_f32 v12, -v12, v41, v39
	v_div_fmas_f32 v12, v12, v13, v41
	v_div_fixup_f32 v11, v12, v11, 1.0
	v_fma_f32 v11, v25, v11, v7
	v_max_f32_e32 v11, 0xda24260, v11
	v_cmp_gt_f32_e32 vcc, s56, v11
	s_nop 1
	v_cndmask_b32_e64 v12, 0, 32, vcc
	v_ldexp_f32 v11, v11, v12
	v_log_f32_e32 v11, v11
	s_nop 0
	v_mul_f32_e32 v12, 0x3f317217, v11
	v_fma_f32 v12, v11, s57, -v12
	v_fmac_f32_e32 v12, 0x3377d1cf, v11
	v_fmac_f32_e32 v12, 0x3f317217, v11
	v_cmp_lt_f32_e64 s[0:1], |v11|, s8
	s_nop 1
	v_cndmask_b32_e64 v11, v11, v12, s[0:1]
	v_cndmask_b32_e32 v12, 0, v201, vcc
	v_sub_f32_e32 v11, v11, v12
	v_mul_f32_e32 v12, 0xbfb8aa3b, v43
	v_exp_f32_e32 v12, v12
	s_nop 0
	v_add_f32_e32 v12, 1.0, v12
	v_div_scale_f32 v13, s[0:1], v12, v12, 1.0
	v_rcp_f32_e32 v39, v13
	s_nop 0
	v_fma_f32 v41, -v13, v39, 1.0
	v_fmac_f32_e32 v39, v41, v39
	v_div_scale_f32 v41, vcc, 1.0, v12, 1.0
	v_mul_f32_e32 v43, v41, v39
	v_fma_f32 v64, -v13, v43, v41
	v_fmac_f32_e32 v43, v64, v39
	v_fma_f32 v13, -v13, v43, v41
	v_div_fmas_f32 v13, v13, v39, v43
	v_div_fixup_f32 v12, v13, v12, 1.0
	v_fma_f32 v12, v24, v12, v8
	v_max_f32_e32 v12, 0xda24260, v12
	v_cmp_gt_f32_e32 vcc, s56, v12
	s_nop 1
	v_cndmask_b32_e64 v13, 0, 32, vcc
	v_ldexp_f32 v12, v12, v13
	v_log_f32_e32 v12, v12
	s_nop 0
	v_mul_f32_e32 v13, 0x3f317217, v12
	v_fma_f32 v13, v12, s57, -v13
	v_fmac_f32_e32 v13, 0x3377d1cf, v12
	v_fmac_f32_e32 v13, 0x3f317217, v12
	v_cmp_lt_f32_e64 s[0:1], |v12|, s8
	s_nop 1
	v_cndmask_b32_e64 v12, v12, v13, s[0:1]
	v_cndmask_b32_e32 v13, 0, v201, vcc
	v_sub_f32_e32 v12, v12, v13
	v_mul_f32_e32 v13, 0xbfb8aa3b, v45
	v_exp_f32_e32 v13, v13
	s_nop 0
	v_add_f32_e32 v13, 1.0, v13
	v_div_scale_f32 v39, s[0:1], v13, v13, 1.0
	v_rcp_f32_e32 v41, v39
	s_nop 0
	v_fma_f32 v43, -v39, v41, 1.0
	v_fmac_f32_e32 v41, v43, v41
	v_div_scale_f32 v43, vcc, 1.0, v13, 1.0
	v_mul_f32_e32 v45, v43, v41
	v_fma_f32 v64, -v39, v45, v43
	v_fmac_f32_e32 v45, v64, v41
	v_fma_f32 v39, -v39, v45, v43
	v_div_fmas_f32 v39, v39, v41, v45
	v_div_fixup_f32 v13, v39, v13, 1.0
	v_fma_f32 v13, v23, v13, v9
	v_max_f32_e32 v13, 0xda24260, v13
	v_cmp_gt_f32_e32 vcc, s56, v13
	s_nop 1
	v_cndmask_b32_e64 v39, 0, 32, vcc
	v_ldexp_f32 v13, v13, v39
	v_log_f32_e32 v13, v13
	s_nop 0
	v_mul_f32_e32 v39, 0x3f317217, v13
	v_fma_f32 v39, v13, s57, -v39
	v_fmac_f32_e32 v39, 0x3377d1cf, v13
	v_fmac_f32_e32 v39, 0x3f317217, v13
	v_cmp_lt_f32_e64 s[0:1], |v13|, s8
	s_nop 1
	v_cndmask_b32_e64 v13, v13, v39, s[0:1]
	v_cndmask_b32_e32 v39, 0, v201, vcc
	v_sub_f32_e32 v13, v13, v39
	v_mul_f32_e32 v39, 0xbfb8aa3b, v62
	v_exp_f32_e32 v39, v39
	s_nop 0
	v_add_f32_e32 v39, 1.0, v39
	v_div_scale_f32 v41, s[0:1], v39, v39, 1.0
	v_rcp_f32_e32 v43, v41
	s_nop 0
	v_fma_f32 v45, -v41, v43, 1.0
	v_fmac_f32_e32 v43, v45, v43
	v_div_scale_f32 v45, vcc, 1.0, v39, 1.0
	v_mul_f32_e32 v62, v45, v43
	v_fma_f32 v64, -v41, v62, v45
	v_fmac_f32_e32 v62, v64, v43
	v_fma_f32 v41, -v41, v62, v45
	v_div_fmas_f32 v41, v41, v43, v62
	v_div_fixup_f32 v39, v41, v39, 1.0
	v_fma_f32 v39, v22, v39, v2
	v_max_f32_e32 v39, 0xda24260, v39
	v_cmp_gt_f32_e32 vcc, s56, v39
	s_nop 1
	v_cndmask_b32_e64 v41, 0, 32, vcc
	v_ldexp_f32 v39, v39, v41
	v_log_f32_e32 v39, v39
	s_nop 0
	v_mul_f32_e32 v41, 0x3f317217, v39
	v_fma_f32 v41, v39, s57, -v41
	v_fmac_f32_e32 v41, 0x3377d1cf, v39
	v_fmac_f32_e32 v41, 0x3f317217, v39
	v_cmp_lt_f32_e64 s[0:1], |v39|, s8
	s_nop 1
	v_cndmask_b32_e64 v39, v39, v41, s[0:1]
	v_cndmask_b32_e32 v41, 0, v201, vcc
	v_sub_f32_e32 v62, v39, v41
	v_mul_f32_e32 v39, 0xbfb8aa3b, v63
	v_exp_f32_e32 v39, v39
	s_nop 0
	v_add_f32_e32 v39, 1.0, v39
	v_div_scale_f32 v41, s[0:1], v39, v39, 1.0
	v_rcp_f32_e32 v43, v41
	s_nop 0
	v_fma_f32 v45, -v41, v43, 1.0
	v_fmac_f32_e32 v43, v45, v43
	v_div_scale_f32 v45, vcc, 1.0, v39, 1.0
	v_mul_f32_e32 v63, v45, v43
	v_fma_f32 v64, -v41, v63, v45
; __device__ __forceinline__ float sigmoidf_(float x) { return 1.0f / (1.0f + __expf(-x)); }
; __device__ __forceinline__ void hg_bcum(const Params& p, int l, const u16* Uhg, int t0, int h, float* bc, float* lbs,
;                                         float* tots) {
;     ...
;   for (int k = 0; k < 4; ++k) {
;     const int s = (tid >> 4) + 16 * k, d0 = (tid & 15) * 8;
;     float z[8];
;     unpack8(*(const uint4*)(Uhg + (size_t)(t0 + s) * 2048 + 512 + h * 128 + d0), z);
;     float lf[8];
; #pragma unroll
;     for (int j = 0; j < 8; ++j) {
;       const float lbv = lbs[d0 + j];
;       const float f = lbv + (1.0f - lbv) * sigmoidf_(z[j]);
;       lf[j] = __logf(fmaxf(f, 1e-30f));
;     }
;     *(float4*)(bc + s * BCS + d0) = make_float4(lf[0], lf[1], lf[2], lf[3]);
;     *(float4*)(bc + s * BCS + d0 + 4) = make_float4(lf[4], lf[5], lf[6], lf[7]);
	v_fmac_f32_e32 v63, v64, v43
	v_fma_f32 v41, -v41, v63, v45
	v_div_fmas_f32 v41, v41, v43, v63
	v_div_fixup_f32 v39, v41, v39, 1.0
	v_fma_f32 v39, v21, v39, v3
	v_max_f32_e32 v39, 0xda24260, v39
	v_cmp_gt_f32_e32 vcc, s56, v39
	s_nop 1
	v_cndmask_b32_e64 v41, 0, 32, vcc
	v_ldexp_f32 v39, v39, v41
	v_log_f32_e32 v39, v39
	s_nop 0
	v_mul_f32_e32 v41, 0x3f317217, v39
	v_fma_f32 v41, v39, s57, -v41
	v_fmac_f32_e32 v41, 0x3377d1cf, v39
	v_fmac_f32_e32 v41, 0x3f317217, v39
	v_cmp_lt_f32_e64 s[0:1], |v39|, s8
	s_nop 1
	v_cndmask_b32_e64 v39, v39, v41, s[0:1]
	v_cndmask_b32_e32 v41, 0, v201, vcc
	v_sub_f32_e32 v63, v39, v41
	v_div_scale_f32 v39, s[0:1], v37, v37, 1.0
	v_rcp_f32_e32 v41, v39
	s_nop 0
	v_fma_f32 v43, -v39, v41, 1.0
	v_fmac_f32_e32 v41, v43, v41
	v_div_scale_f32 v43, vcc, 1.0, v37, 1.0
	v_mul_f32_e32 v45, v43, v41
	v_fma_f32 v64, -v39, v45, v43
	v_fmac_f32_e32 v45, v64, v41
	v_fma_f32 v39, -v39, v45, v43
	v_div_fmas_f32 v39, v39, v41, v45
	v_div_fixup_f32 v37, v39, v37, 1.0
	v_fma_f32 v37, v20, v37, v4
	v_max_f32_e32 v37, 0xda24260, v37
	v_cmp_gt_f32_e32 vcc, s56, v37
	s_nop 1
	v_cndmask_b32_e64 v39, 0, 32, vcc
	v_ldexp_f32 v37, v37, v39
	v_log_f32_e32 v37, v37
	s_nop 0
	v_mul_f32_e32 v39, 0x3f317217, v37
	v_fma_f32 v39, v37, s57, -v39
	v_fmac_f32_e32 v39, 0x3377d1cf, v37
	v_fmac_f32_e32 v39, 0x3f317217, v37
	v_cmp_lt_f32_e64 s[0:1], |v37|, s8
	s_nop 1
	v_cndmask_b32_e64 v37, v37, v39, s[0:1]
	v_cndmask_b32_e32 v39, 0, v201, vcc
	v_sub_f32_e32 v64, v37, v39
	v_div_scale_f32 v37, s[0:1], v35, v35, 1.0
	v_rcp_f32_e32 v39, v37
	s_nop 0
	v_fma_f32 v41, -v37, v39, 1.0
	v_fmac_f32_e32 v39, v41, v39
	v_div_scale_f32 v41, vcc, 1.0, v35, 1.0
	v_mul_f32_e32 v43, v41, v39
	v_fma_f32 v45, -v37, v43, v41
	v_fmac_f32_e32 v43, v45, v39
	v_fma_f32 v37, -v37, v43, v41
	v_div_fmas_f32 v37, v37, v39, v43
	v_div_fixup_f32 v35, v37, v35, 1.0
	v_fma_f32 v35, v19, v35, v5
	v_max_f32_e32 v35, 0xda24260, v35
	v_cmp_gt_f32_e32 vcc, s56, v35
	s_nop 1
	v_cndmask_b32_e64 v37, 0, 32, vcc
	v_ldexp_f32 v35, v35, v37
	v_log_f32_e32 v35, v35
	s_nop 0
	v_mul_f32_e32 v37, 0x3f317217, v35
	v_fma_f32 v37, v35, s57, -v37
	v_fmac_f32_e32 v37, 0x3377d1cf, v35
	v_fmac_f32_e32 v37, 0x3f317217, v35
	v_cmp_lt_f32_e64 s[0:1], |v35|, s8
	s_nop 1
	v_cndmask_b32_e64 v35, v35, v37, s[0:1]
	v_cndmask_b32_e32 v37, 0, v201, vcc
	v_sub_f32_e32 v65, v35, v37
	ds_write_b128 v15, v[10:13] offset:8448
	ds_write_b128 v15, v[62:65] offset:8464
	v_or_b32_e32 v10, 32, v14
	v_ashrrev_i32_e32 v11, 31, v10
	v_lshlrev_b64 v[10:11], 12, v[10:11]
	v_lshl_add_u64 v[10:11], s[22:23], 0, v[10:11]
	v_lshl_add_u64 v[10:11], v[10:11], 0, s[58:59]
	v_lshl_add_u64 v[10:11], v[10:11], 0, v[16:17]
	s_waitcnt vmcnt(1)
	v_mov_b64_e32 v[10:11], v[162:163]
	v_mov_b64_e32 v[12:13], v[164:165]
	v_lshlrev_b32_e32 v35, 16, v10
	v_and_b32_e32 v37, 0xffff0000, v10
	v_mul_f32_e32 v10, 0xbfb8aa3b, v35
	v_exp_f32_e32 v10, v10
	v_lshlrev_b32_e32 v39, 16, v11
	v_and_b32_e32 v41, 0xffff0000, v11
	v_lshlrev_b32_e32 v43, 16, v12
	v_add_f32_e32 v10, 1.0, v10
	v_div_scale_f32 v11, s[0:1], v10, v10, 1.0
	v_and_b32_e32 v45, 0xffff0000, v12
	v_rcp_f32_e32 v12, v11
	v_lshlrev_b32_e32 v64, 16, v13
	v_and_b32_e32 v65, 0xffff0000, v13
	v_fma_f32 v13, -v11, v12, 1.0
	v_fmac_f32_e32 v12, v13, v12
	v_div_scale_f32 v13, vcc, 1.0, v10, 1.0
	v_mul_f32_e32 v35, v13, v12
	v_fma_f32 v62, -v11, v35, v13
	v_fmac_f32_e32 v35, v62, v12
	v_fma_f32 v11, -v11, v35, v13
	v_div_fmas_f32 v11, v11, v12, v35
	v_div_fixup_f32 v10, v11, v10, 1.0
	v_fma_f32 v10, v33, v10, v6
	v_max_f32_e32 v10, 0xda24260, v10
	v_cmp_gt_f32_e32 vcc, s56, v10
	s_nop 1
	v_cndmask_b32_e64 v11, 0, 32, vcc
	v_ldexp_f32 v10, v10, v11
	v_log_f32_e32 v10, v10
	s_nop 0
	v_mul_f32_e32 v11, 0x3f317217, v10
	v_fma_f32 v11, v10, s57, -v11
	v_fmac_f32_e32 v11, 0x3377d1cf, v10
	v_fmac_f32_e32 v11, 0x3f317217, v10
	v_cmp_lt_f32_e64 s[0:1], |v10|, s8
	s_nop 1
	v_cndmask_b32_e64 v10, v10, v11, s[0:1]
	v_cndmask_b32_e32 v11, 0, v201, vcc
	v_sub_f32_e32 v10, v10, v11
	v_mul_f32_e32 v11, 0xbfb8aa3b, v37
	v_exp_f32_e32 v11, v11
	s_nop 0
	v_add_f32_e32 v11, 1.0, v11
	v_div_scale_f32 v12, s[0:1], v11, v11, 1.0
	v_rcp_f32_e32 v13, v12
	s_nop 0
	v_fma_f32 v35, -v12, v13, 1.0
	v_fmac_f32_e32 v13, v35, v13
	v_div_scale_f32 v35, vcc, 1.0, v11, 1.0
	v_mul_f32_e32 v37, v35, v13
	v_fma_f32 v62, -v12, v37, v35
	v_fmac_f32_e32 v37, v62, v13
	v_fma_f32 v12, -v12, v37, v35
	v_div_fmas_f32 v12, v12, v13, v37
	v_div_fixup_f32 v11, v12, v11, 1.0
	v_fma_f32 v11, v25, v11, v7
	v_max_f32_e32 v11, 0xda24260, v11
	v_cmp_gt_f32_e32 vcc, s56, v11
	s_nop 1
	v_cndmask_b32_e64 v12, 0, 32, vcc
	v_ldexp_f32 v11, v11, v12
	v_log_f32_e32 v11, v11
	s_nop 0
	v_mul_f32_e32 v12, 0x3f317217, v11
	v_fma_f32 v12, v11, s57, -v12
	v_fmac_f32_e32 v12, 0x3377d1cf, v11
	v_fmac_f32_e32 v12, 0x3f317217, v11
	v_cmp_lt_f32_e64 s[0:1], |v11|, s8
	s_nop 1
	v_cndmask_b32_e64 v11, v11, v12, s[0:1]
	v_cndmask_b32_e32 v12, 0, v201, vcc
	v_sub_f32_e32 v11, v11, v12
	v_mul_f32_e32 v12, 0xbfb8aa3b, v39
	v_exp_f32_e32 v12, v12
	s_nop 0
	v_add_f32_e32 v12, 1.0, v12
	v_div_scale_f32 v13, s[0:1], v12, v12, 1.0
	v_rcp_f32_e32 v35, v13
	s_nop 0
	v_fma_f32 v37, -v13, v35, 1.0
	v_fmac_f32_e32 v35, v37, v35
	v_div_scale_f32 v37, vcc, 1.0, v12, 1.0
	v_mul_f32_e32 v39, v37, v35
	v_fma_f32 v62, -v13, v39, v37
	v_fmac_f32_e32 v39, v62, v35
	v_fma_f32 v13, -v13, v39, v37
	v_div_fmas_f32 v13, v13, v35, v39
	v_div_fixup_f32 v12, v13, v12, 1.0
	v_fma_f32 v12, v24, v12, v8
	v_max_f32_e32 v12, 0xda24260, v12
	v_cmp_gt_f32_e32 vcc, s56, v12
	s_nop 1
	v_cndmask_b32_e64 v13, 0, 32, vcc
	v_ldexp_f32 v12, v12, v13
	v_log_f32_e32 v12, v12
	s_nop 0
	v_mul_f32_e32 v13, 0x3f317217, v12
; __device__ __forceinline__ float sigmoidf_(float x) { return 1.0f / (1.0f + __expf(-x)); }
; __device__ __forceinline__ void hg_bcum(const Params& p, int l, const u16* Uhg, int t0, int h, float* bc, float* lbs,
;                                         float* tots) {
;     ...
;   for (int k = 0; k < 4; ++k) {
;     const int s = (tid >> 4) + 16 * k, d0 = (tid & 15) * 8;
;     float z[8];
;     unpack8(*(const uint4*)(Uhg + (size_t)(t0 + s) * 2048 + 512 + h * 128 + d0), z);
;     float lf[8];
; #pragma unroll
;     for (int j = 0; j < 8; ++j) {
;       const float lbv = lbs[d0 + j];
;       const float f = lbv + (1.0f - lbv) * sigmoidf_(z[j]);
;       lf[j] = __logf(fmaxf(f, 1e-30f));
;     }
;     *(float4*)(bc + s * BCS + d0) = make_float4(lf[0], lf[1], lf[2], lf[3]);
;     *(float4*)(bc + s * BCS + d0 + 4) = make_float4(lf[4], lf[5], lf[6], lf[7]);
	v_fma_f32 v13, v12, s57, -v13
	v_fmac_f32_e32 v13, 0x3377d1cf, v12
	v_fmac_f32_e32 v13, 0x3f317217, v12
	v_cmp_lt_f32_e64 s[0:1], |v12|, s8
	s_nop 1
	v_cndmask_b32_e64 v12, v12, v13, s[0:1]
	v_cndmask_b32_e32 v13, 0, v201, vcc
	v_sub_f32_e32 v12, v12, v13
	v_mul_f32_e32 v13, 0xbfb8aa3b, v41
	v_exp_f32_e32 v13, v13
	s_nop 0
	v_add_f32_e32 v13, 1.0, v13
	v_div_scale_f32 v35, s[0:1], v13, v13, 1.0
	v_rcp_f32_e32 v37, v35
	s_nop 0
	v_fma_f32 v39, -v35, v37, 1.0
	v_fmac_f32_e32 v37, v39, v37
	v_div_scale_f32 v39, vcc, 1.0, v13, 1.0
	v_mul_f32_e32 v41, v39, v37
	v_fma_f32 v62, -v35, v41, v39
	v_fmac_f32_e32 v41, v62, v37
	v_fma_f32 v35, -v35, v41, v39
	v_div_fmas_f32 v35, v35, v37, v41
	v_div_fixup_f32 v13, v35, v13, 1.0
	v_fma_f32 v13, v23, v13, v9
	v_max_f32_e32 v13, 0xda24260, v13
	v_cmp_gt_f32_e32 vcc, s56, v13
	s_nop 1
	v_cndmask_b32_e64 v35, 0, 32, vcc
	v_ldexp_f32 v13, v13, v35
	v_log_f32_e32 v13, v13
	s_nop 0
	v_mul_f32_e32 v35, 0x3f317217, v13
	v_fma_f32 v35, v13, s57, -v35
	v_fmac_f32_e32 v35, 0x3377d1cf, v13
	v_fmac_f32_e32 v35, 0x3f317217, v13
	v_cmp_lt_f32_e64 s[0:1], |v13|, s8
	s_nop 1
	v_cndmask_b32_e64 v13, v13, v35, s[0:1]
	v_cndmask_b32_e32 v35, 0, v201, vcc
	v_sub_f32_e32 v13, v13, v35
	v_mul_f32_e32 v35, 0xbfb8aa3b, v43
	v_exp_f32_e32 v35, v35
	s_nop 0
	v_add_f32_e32 v35, 1.0, v35
	v_div_scale_f32 v37, s[0:1], v35, v35, 1.0
	v_rcp_f32_e32 v39, v37
	s_nop 0
	v_fma_f32 v41, -v37, v39, 1.0
	v_fmac_f32_e32 v39, v41, v39
	v_div_scale_f32 v41, vcc, 1.0, v35, 1.0
	v_mul_f32_e32 v43, v41, v39
	v_fma_f32 v62, -v37, v43, v41
	v_fmac_f32_e32 v43, v62, v39
	v_fma_f32 v37, -v37, v43, v41
	v_div_fmas_f32 v37, v37, v39, v43
	v_div_fixup_f32 v35, v37, v35, 1.0
	v_fma_f32 v35, v22, v35, v2
	v_max_f32_e32 v35, 0xda24260, v35
	v_cmp_gt_f32_e32 vcc, s56, v35
	s_nop 1
	v_cndmask_b32_e64 v37, 0, 32, vcc
	v_ldexp_f32 v35, v35, v37
	v_log_f32_e32 v35, v35
	s_nop 0
	v_mul_f32_e32 v37, 0x3f317217, v35
	v_fma_f32 v37, v35, s57, -v37
	v_fmac_f32_e32 v37, 0x3377d1cf, v35
	v_fmac_f32_e32 v37, 0x3f317217, v35
	v_cmp_lt_f32_e64 s[0:1], |v35|, s8
	s_nop 1
	v_cndmask_b32_e64 v35, v35, v37, s[0:1]
	v_cndmask_b32_e32 v37, 0, v201, vcc
	v_sub_f32_e32 v62, v35, v37
	v_mul_f32_e32 v35, 0xbfb8aa3b, v45
	v_exp_f32_e32 v35, v35
	s_nop 0
	v_add_f32_e32 v35, 1.0, v35
	v_div_scale_f32 v37, s[0:1], v35, v35, 1.0
	v_rcp_f32_e32 v39, v37
	s_nop 0
	v_fma_f32 v41, -v37, v39, 1.0
	v_fmac_f32_e32 v39, v41, v39
	v_div_scale_f32 v41, vcc, 1.0, v35, 1.0
	v_mul_f32_e32 v43, v41, v39
	v_fma_f32 v45, -v37, v43, v41
	v_fmac_f32_e32 v43, v45, v39
	v_fma_f32 v37, -v37, v43, v41
	v_div_fmas_f32 v37, v37, v39, v43
	v_div_fixup_f32 v35, v37, v35, 1.0
	v_fma_f32 v35, v21, v35, v3
	v_max_f32_e32 v35, 0xda24260, v35
	v_cmp_gt_f32_e32 vcc, s56, v35
	s_nop 1
	v_cndmask_b32_e64 v37, 0, 32, vcc
	v_ldexp_f32 v35, v35, v37
	v_log_f32_e32 v35, v35
	s_nop 0
	v_mul_f32_e32 v37, 0x3f317217, v35
	v_fma_f32 v37, v35, s57, -v37
	v_fmac_f32_e32 v37, 0x3377d1cf, v35
	v_fmac_f32_e32 v37, 0x3f317217, v35
	v_cmp_lt_f32_e64 s[0:1], |v35|, s8
	s_nop 1
	v_cndmask_b32_e64 v35, v35, v37, s[0:1]
	v_cndmask_b32_e32 v37, 0, v201, vcc
	v_sub_f32_e32 v63, v35, v37
	v_mul_f32_e32 v35, 0xbfb8aa3b, v64
	v_exp_f32_e32 v35, v35
	s_nop 0
	v_add_f32_e32 v35, 1.0, v35
	v_div_scale_f32 v37, s[0:1], v35, v35, 1.0
	v_rcp_f32_e32 v39, v37
	s_nop 0
	v_fma_f32 v41, -v37, v39, 1.0
	v_fmac_f32_e32 v39, v41, v39
	v_div_scale_f32 v41, vcc, 1.0, v35, 1.0
	v_mul_f32_e32 v43, v41, v39
	v_fma_f32 v45, -v37, v43, v41
	v_fmac_f32_e32 v43, v45, v39
	v_fma_f32 v37, -v37, v43, v41
	v_div_fmas_f32 v37, v37, v39, v43
	v_div_fixup_f32 v35, v37, v35, 1.0
	v_fma_f32 v35, v20, v35, v4
	v_max_f32_e32 v35, 0xda24260, v35
	v_cmp_gt_f32_e32 vcc, s56, v35
	s_nop 1
	v_cndmask_b32_e64 v37, 0, 32, vcc
	v_ldexp_f32 v35, v35, v37
	v_log_f32_e32 v35, v35
	s_nop 0
	v_mul_f32_e32 v37, 0x3f317217, v35
	v_fma_f32 v37, v35, s57, -v37
	v_fmac_f32_e32 v37, 0x3377d1cf, v35
	v_fmac_f32_e32 v37, 0x3f317217, v35
	v_cmp_lt_f32_e64 s[0:1], |v35|, s8
	s_nop 1
	v_cndmask_b32_e64 v35, v35, v37, s[0:1]
	v_cndmask_b32_e32 v37, 0, v201, vcc
	v_sub_f32_e32 v64, v35, v37
	v_mul_f32_e32 v35, 0xbfb8aa3b, v65
	v_exp_f32_e32 v35, v35
	s_nop 0
	v_add_f32_e32 v35, 1.0, v35
	v_div_scale_f32 v37, s[0:1], v35, v35, 1.0
	v_rcp_f32_e32 v39, v37
	s_nop 0
	v_fma_f32 v41, -v37, v39, 1.0
	v_fmac_f32_e32 v39, v41, v39
	v_div_scale_f32 v41, vcc, 1.0, v35, 1.0
	v_mul_f32_e32 v43, v41, v39
	v_fma_f32 v45, -v37, v43, v41
	v_fmac_f32_e32 v43, v45, v39
	v_fma_f32 v37, -v37, v43, v41
	v_div_fmas_f32 v37, v37, v39, v43
	v_div_fixup_f32 v35, v37, v35, 1.0
	v_fma_f32 v35, v19, v35, v5
	v_max_f32_e32 v35, 0xda24260, v35
	v_cmp_gt_f32_e32 vcc, s56, v35
	s_nop 1
	v_cndmask_b32_e64 v37, 0, 32, vcc
	v_ldexp_f32 v35, v35, v37
	v_log_f32_e32 v35, v35
	s_nop 0
	v_mul_f32_e32 v37, 0x3f317217, v35
	v_fma_f32 v37, v35, s57, -v37
	v_fmac_f32_e32 v37, 0x3377d1cf, v35
	v_fmac_f32_e32 v37, 0x3f317217, v35
	v_cmp_lt_f32_e64 s[0:1], |v35|, s8
	s_nop 1
	v_cndmask_b32_e64 v35, v35, v37, s[0:1]
	v_cndmask_b32_e32 v37, 0, v201, vcc
	v_sub_f32_e32 v65, v35, v37
	ds_write_b128 v15, v[10:13] offset:16896
	ds_write_b128 v15, v[62:65] offset:16912
	v_or_b32_e32 v10, 48, v14
	v_ashrrev_i32_e32 v11, 31, v10
	v_lshlrev_b64 v[10:11], 12, v[10:11]
	v_lshl_add_u64 v[10:11], s[22:23], 0, v[10:11]
	v_lshl_add_u64 v[10:11], v[10:11], 0, s[58:59]
	v_lshl_add_u64 v[10:11], v[10:11], 0, v[16:17]
	s_waitcnt vmcnt(0)
; __device__ __forceinline__ float sigmoidf_(float x) { return 1.0f / (1.0f + __expf(-x)); }
; __device__ __forceinline__ void hg_bcum(const Params& p, int l, const u16* Uhg, int t0, int h, float* bc, float* lbs,
;                                         float* tots) {
;     ...
;   for (int k = 0; k < 4; ++k) {
;     const int s = (tid >> 4) + 16 * k, d0 = (tid & 15) * 8;
;     float z[8];
;     unpack8(*(const uint4*)(Uhg + (size_t)(t0 + s) * 2048 + 512 + h * 128 + d0), z);
;     float lf[8];
; #pragma unroll
;     for (int j = 0; j < 8; ++j) {
;       const float lbv = lbs[d0 + j];
;       const float f = lbv + (1.0f - lbv) * sigmoidf_(z[j]);
;       lf[j] = __logf(fmaxf(f, 1e-30f));
;     }
;     *(float4*)(bc + s * BCS + d0) = make_float4(lf[0], lf[1], lf[2], lf[3]);
;     *(float4*)(bc + s * BCS + d0 + 4) = make_float4(lf[4], lf[5], lf[6], lf[7]);
	v_mov_b64_e32 v[10:11], v[166:167]
	v_mov_b64_e32 v[12:13], v[168:169]
	v_lshlrev_b32_e32 v14, 16, v10
	v_and_b32_e32 v16, 0xffff0000, v10
	v_lshlrev_b32_e32 v17, 16, v11
	v_and_b32_e32 v35, 0xffff0000, v11
	v_lshlrev_b32_e32 v11, 16, v13
	v_and_b32_e32 v10, 0xffff0000, v13
	v_mul_f32_e32 v13, 0xbfb8aa3b, v14
	v_exp_f32_e32 v13, v13
	v_lshlrev_b32_e32 v37, 16, v12
	v_and_b32_e32 v12, 0xffff0000, v12
	v_mul_f32_e32 v12, 0xbfb8aa3b, v12
	v_add_f32_e32 v13, 1.0, v13
	v_div_scale_f32 v14, s[0:1], v13, v13, 1.0
	v_rcp_f32_e32 v39, v14
	v_exp_f32_e32 v12, v12
	v_mul_f32_e32 v11, 0xbfb8aa3b, v11
	v_exp_f32_e32 v11, v11
	v_fma_f32 v41, -v14, v39, 1.0
	v_fmac_f32_e32 v39, v41, v39
	v_div_scale_f32 v41, vcc, 1.0, v13, 1.0
	v_mul_f32_e32 v43, v41, v39
	v_fma_f32 v45, -v14, v43, v41
	v_fmac_f32_e32 v43, v45, v39
	v_fma_f32 v14, -v14, v43, v41
	v_div_fmas_f32 v14, v14, v39, v43
	v_div_fixup_f32 v13, v14, v13, 1.0
	v_fma_f32 v6, v33, v13, v6
	v_max_f32_e32 v6, 0xda24260, v6
	v_cmp_gt_f32_e32 vcc, s56, v6
	v_add_f32_e32 v12, 1.0, v12
	v_add_f32_e32 v11, 1.0, v11
	v_cndmask_b32_e64 v13, 0, 32, vcc
	v_ldexp_f32 v6, v6, v13
	v_log_f32_e32 v6, v6
	v_mul_f32_e32 v10, 0xbfb8aa3b, v10
	v_exp_f32_e32 v10, v10
	v_mul_f32_e32 v13, 0x3f317217, v6
	v_fma_f32 v13, v6, s57, -v13
	v_fmac_f32_e32 v13, 0x3377d1cf, v6
	v_fmac_f32_e32 v13, 0x3f317217, v6
	v_cmp_lt_f32_e64 s[0:1], |v6|, s8
	v_add_f32_e32 v10, 1.0, v10
	s_nop 0
	v_cndmask_b32_e64 v6, v6, v13, s[0:1]
	v_cndmask_b32_e32 v13, 0, v201, vcc
	v_sub_f32_e32 v6, v6, v13
	v_mul_f32_e32 v13, 0xbfb8aa3b, v16
	v_exp_f32_e32 v13, v13
	s_nop 0
	v_add_f32_e32 v13, 1.0, v13
	v_div_scale_f32 v14, s[0:1], v13, v13, 1.0
	v_rcp_f32_e32 v16, v14
	s_nop 0
	v_fma_f32 v33, -v14, v16, 1.0
	v_fmac_f32_e32 v16, v33, v16
	v_div_scale_f32 v33, vcc, 1.0, v13, 1.0
	v_mul_f32_e32 v39, v33, v16
	v_fma_f32 v41, -v14, v39, v33
	v_fmac_f32_e32 v39, v41, v16
	v_fma_f32 v14, -v14, v39, v33
	v_div_fmas_f32 v14, v14, v16, v39
	v_div_fixup_f32 v13, v14, v13, 1.0
	v_fma_f32 v7, v25, v13, v7
	v_max_f32_e32 v7, 0xda24260, v7
	v_cmp_gt_f32_e32 vcc, s56, v7
	s_nop 1
	v_cndmask_b32_e64 v13, 0, 32, vcc
	v_ldexp_f32 v7, v7, v13
	v_log_f32_e32 v7, v7
	s_nop 0
	v_mul_f32_e32 v13, 0x3f317217, v7
	v_fma_f32 v13, v7, s57, -v13
	v_fmac_f32_e32 v13, 0x3377d1cf, v7
	v_fmac_f32_e32 v13, 0x3f317217, v7
	v_cmp_lt_f32_e64 s[0:1], |v7|, s8
	s_nop 1
	v_cndmask_b32_e64 v7, v7, v13, s[0:1]
	v_cndmask_b32_e32 v13, 0, v201, vcc
	v_sub_f32_e32 v7, v7, v13
	v_mul_f32_e32 v13, 0xbfb8aa3b, v17
	v_exp_f32_e32 v13, v13
	s_nop 0
	v_add_f32_e32 v13, 1.0, v13
	v_div_scale_f32 v14, s[0:1], v13, v13, 1.0
	v_rcp_f32_e32 v16, v14
	s_nop 0
	v_fma_f32 v17, -v14, v16, 1.0
	v_fmac_f32_e32 v16, v17, v16
	v_div_scale_f32 v17, vcc, 1.0, v13, 1.0
	v_mul_f32_e32 v25, v17, v16
	v_fma_f32 v33, -v14, v25, v17
	v_fmac_f32_e32 v25, v33, v16
	v_fma_f32 v14, -v14, v25, v17
	v_div_fmas_f32 v14, v14, v16, v25
	v_div_fixup_f32 v13, v14, v13, 1.0
	v_fma_f32 v8, v24, v13, v8
	v_max_f32_e32 v8, 0xda24260, v8
	v_cmp_gt_f32_e32 vcc, s56, v8
	s_nop 1
	v_cndmask_b32_e64 v13, 0, 32, vcc
	v_ldexp_f32 v8, v8, v13
	v_log_f32_e32 v8, v8
	s_nop 0
	v_mul_f32_e32 v13, 0x3f317217, v8
	v_fma_f32 v13, v8, s57, -v13
	v_fmac_f32_e32 v13, 0x3377d1cf, v8
	v_fmac_f32_e32 v13, 0x3f317217, v8
	v_cmp_lt_f32_e64 s[0:1], |v8|, s8
	s_nop 1
	v_cndmask_b32_e64 v8, v8, v13, s[0:1]
	v_cndmask_b32_e32 v13, 0, v201, vcc
	v_sub_f32_e32 v8, v8, v13
	v_mul_f32_e32 v13, 0xbfb8aa3b, v35
	v_exp_f32_e32 v13, v13
	s_nop 0
	v_add_f32_e32 v13, 1.0, v13
	v_div_scale_f32 v14, s[0:1], v13, v13, 1.0
	v_rcp_f32_e32 v16, v14
	s_nop 0
	v_fma_f32 v17, -v14, v16, 1.0
	v_fmac_f32_e32 v16, v17, v16
	v_div_scale_f32 v17, vcc, 1.0, v13, 1.0
	v_mul_f32_e32 v24, v17, v16
	v_fma_f32 v25, -v14, v24, v17
	v_fmac_f32_e32 v24, v25, v16
	v_fma_f32 v14, -v14, v24, v17
	v_div_fmas_f32 v14, v14, v16, v24
	v_div_fixup_f32 v13, v14, v13, 1.0
	v_fmac_f32_e32 v9, v23, v13
	v_max_f32_e32 v9, 0xda24260, v9
	v_cmp_gt_f32_e32 vcc, s56, v9
	s_nop 1
	v_cndmask_b32_e64 v13, 0, 32, vcc
	v_ldexp_f32 v9, v9, v13
	v_log_f32_e32 v9, v9
	s_nop 0
	v_mul_f32_e32 v13, 0x3f317217, v9
	v_fma_f32 v13, v9, s57, -v13
	v_fmac_f32_e32 v13, 0x3377d1cf, v9
	v_fmac_f32_e32 v13, 0x3f317217, v9
	v_cmp_lt_f32_e64 s[0:1], |v9|, s8
	s_nop 1
	v_cndmask_b32_e64 v9, v9, v13, s[0:1]
	v_cndmask_b32_e32 v13, 0, v201, vcc
	v_sub_f32_e32 v9, v9, v13
	v_mul_f32_e32 v13, 0xbfb8aa3b, v37
	v_exp_f32_e32 v13, v13
	s_nop 0
	v_add_f32_e32 v13, 1.0, v13
	v_div_scale_f32 v14, s[0:1], v13, v13, 1.0
	v_rcp_f32_e32 v16, v14
	s_nop 0
	v_fma_f32 v17, -v14, v16, 1.0
	v_fmac_f32_e32 v16, v17, v16
	v_div_scale_f32 v17, vcc, 1.0, v13, 1.0
	v_mul_f32_e32 v23, v17, v16
	v_fma_f32 v24, -v14, v23, v17
	v_fmac_f32_e32 v23, v24, v16
	v_fma_f32 v14, -v14, v23, v17
	v_div_fmas_f32 v14, v14, v16, v23
	v_div_fixup_f32 v13, v14, v13, 1.0
	v_fma_f32 v2, v22, v13, v2
	v_max_f32_e32 v2, 0xda24260, v2
	v_cmp_gt_f32_e32 vcc, s56, v2
	s_nop 1
	v_cndmask_b32_e64 v13, 0, 32, vcc
	v_ldexp_f32 v2, v2, v13
	v_log_f32_e32 v2, v2
	s_nop 0
	v_mul_f32_e32 v13, 0x3f317217, v2
	v_fma_f32 v13, v2, s57, -v13
	v_fmac_f32_e32 v13, 0x3377d1cf, v2
	v_fmac_f32_e32 v13, 0x3f317217, v2
	v_cmp_lt_f32_e64 s[0:1], |v2|, s8
	s_nop 1
	v_cndmask_b32_e64 v2, v2, v13, s[0:1]
	v_cndmask_b32_e32 v13, 0, v201, vcc
	v_sub_f32_e32 v2, v2, v13
	v_div_scale_f32 v13, s[0:1], v12, v12, 1.0
	v_rcp_f32_e32 v14, v13
	s_nop 0
	v_fma_f32 v16, -v13, v14, 1.0
	v_fmac_f32_e32 v14, v16, v14
	v_div_scale_f32 v16, vcc, 1.0, v12, 1.0
	v_mul_f32_e32 v17, v16, v14
	v_fma_f32 v22, -v13, v17, v16
	v_fmac_f32_e32 v17, v22, v14
	v_fma_f32 v13, -v13, v17, v16
	v_div_fmas_f32 v13, v13, v14, v17
; __device__ __forceinline__ void hg_bcum(const Params& p, int l, const u16* Uhg, int t0, int h, float* bc, float* lbs,
;                                         float* tots) {
;     ...
;       lf[j] = __logf(fmaxf(f, 1e-30f));
;     }
;     *(float4*)(bc + s * BCS + d0) = make_float4(lf[0], lf[1], lf[2], lf[3]);
;     *(float4*)(bc + s * BCS + d0 + 4) = make_float4(lf[4], lf[5], lf[6], lf[7]);
;   }
;   __syncthreads();
;   {
;     const int d = tid & 127, hf = tid >> 7;
;     float r[32];
;     float run = 0.f;
; #pragma unroll
;     for (int s = 0; s < 32; ++s) { run += bc[(hf * 32 + s) * BCS + d]; r[s] = run; }
;     if (hf == 0) tots[d] = run;
	v_div_fixup_f32 v12, v13, v12, 1.0
	v_fma_f32 v3, v21, v12, v3
	v_max_f32_e32 v3, 0xda24260, v3
	v_cmp_gt_f32_e32 vcc, s56, v3
	s_nop 1
	v_cndmask_b32_e64 v12, 0, 32, vcc
	v_ldexp_f32 v3, v3, v12
	v_log_f32_e32 v3, v3
	s_nop 0
	v_mul_f32_e32 v12, 0x3f317217, v3
	v_fma_f32 v12, v3, s57, -v12
	v_fmac_f32_e32 v12, 0x3377d1cf, v3
	v_fmac_f32_e32 v12, 0x3f317217, v3
	v_cmp_lt_f32_e64 s[0:1], |v3|, s8
	s_nop 1
	v_cndmask_b32_e64 v3, v3, v12, s[0:1]
	v_cndmask_b32_e32 v12, 0, v201, vcc
	v_sub_f32_e32 v3, v3, v12
	v_div_scale_f32 v12, s[0:1], v11, v11, 1.0
	v_rcp_f32_e32 v13, v12
	s_nop 0
	v_fma_f32 v14, -v12, v13, 1.0
	v_fmac_f32_e32 v13, v14, v13
	v_div_scale_f32 v14, vcc, 1.0, v11, 1.0
	v_mul_f32_e32 v16, v14, v13
	v_fma_f32 v17, -v12, v16, v14
	v_fmac_f32_e32 v16, v17, v13
	v_fma_f32 v12, -v12, v16, v14
	v_div_fmas_f32 v12, v12, v13, v16
	v_div_fixup_f32 v11, v12, v11, 1.0
	v_fma_f32 v4, v20, v11, v4
	v_max_f32_e32 v4, 0xda24260, v4
	v_cmp_gt_f32_e32 vcc, s56, v4
	s_nop 1
	v_cndmask_b32_e64 v11, 0, 32, vcc
	v_ldexp_f32 v4, v4, v11
	v_log_f32_e32 v4, v4
	s_nop 0
	v_mul_f32_e32 v11, 0x3f317217, v4
	v_fma_f32 v11, v4, s57, -v11
	v_fmac_f32_e32 v11, 0x3377d1cf, v4
	v_fmac_f32_e32 v11, 0x3f317217, v4
	v_cmp_lt_f32_e64 s[0:1], |v4|, s8
	s_nop 1
	v_cndmask_b32_e64 v4, v4, v11, s[0:1]
	v_cndmask_b32_e32 v11, 0, v201, vcc
	v_sub_f32_e32 v4, v4, v11
	v_div_scale_f32 v11, s[0:1], v10, v10, 1.0
	v_rcp_f32_e32 v12, v11
	s_nop 0
	v_fma_f32 v13, -v11, v12, 1.0
	v_fmac_f32_e32 v12, v13, v12
	v_div_scale_f32 v13, vcc, 1.0, v10, 1.0
	v_mul_f32_e32 v14, v13, v12
	v_fma_f32 v16, -v11, v14, v13
	v_fmac_f32_e32 v14, v16, v12
	v_fma_f32 v11, -v11, v14, v13
	v_div_fmas_f32 v11, v11, v12, v14
	v_div_fixup_f32 v10, v11, v10, 1.0
	v_fmac_f32_e32 v5, v19, v10
	v_max_f32_e32 v5, 0xda24260, v5
	v_cmp_gt_f32_e32 vcc, s56, v5
	s_nop 1
	v_cndmask_b32_e64 v10, 0, 32, vcc
	v_ldexp_f32 v5, v5, v10
	v_log_f32_e32 v5, v5
	s_nop 0
	v_mul_f32_e32 v10, 0x3f317217, v5
	v_fma_f32 v10, v5, s57, -v10
	v_fmac_f32_e32 v10, 0x3377d1cf, v5
	v_fmac_f32_e32 v10, 0x3f317217, v5
	v_cmp_lt_f32_e64 s[0:1], |v5|, s8
	s_nop 1
	v_cndmask_b32_e64 v5, v5, v10, s[0:1]
	v_cndmask_b32_e32 v10, 0, v201, vcc
	v_sub_f32_e32 v5, v5, v10
	ds_write_b128 v15, v[6:9] offset:25344
	ds_write_b128 v15, v[2:5] offset:25360
	v_lshrrev_b32_e32 v2, 2, v18
	v_and_b32_e32 v2, 32, v2
	v_mul_u32_u24_e32 v2, 0x210, v2
	v_lshlrev_b32_e32 v3, 2, v80
	v_add3_u32 v2, s69, v2, v3
	s_waitcnt lgkmcnt(0)
	s_barrier
	ds_read2_b32 v[4:5], v2 offset1:132
	v_add_u32_e32 v3, 0x400, v2
	ds_read2_b32 v[6:7], v3 offset0:8 offset1:140
	v_add_u32_e32 v8, 0x800, v2
	ds_read2_b32 v[10:11], v8 offset0:16 offset1:148
	s_waitcnt lgkmcnt(2)
	v_add_f32_e32 v4, 0, v4
	v_add_f32_e32 v5, v4, v5
	s_waitcnt lgkmcnt(1)
	v_add_f32_e32 v6, v5, v6
	v_add_f32_e32 v7, v6, v7
	s_waitcnt lgkmcnt(0)
	v_add_f32_e32 v9, v7, v10
	v_add_f32_e32 v10, v9, v11
	v_add_u32_e32 v11, 0xc00, v2
	ds_read2_b32 v[14:15], v11 offset0:24 offset1:156
	v_add_u32_e32 v12, 0x1000, v2
	ds_read2_b32 v[16:17], v12 offset0:32 offset1:164
	v_add_u32_e32 v20, 0x1800, v2
	ds_read2_b32 v[22:23], v20 offset0:48 offset1:180
	s_waitcnt lgkmcnt(2)
	v_add_f32_e32 v13, v10, v14
	v_add_f32_e32 v14, v13, v15
	s_waitcnt lgkmcnt(1)
	v_add_f32_e32 v15, v14, v16
	v_add_f32_e32 v16, v15, v17
	v_add_u32_e32 v17, 0x1400, v2
	ds_read2_b32 v[18:19], v17 offset0:40 offset1:172
	v_add_u32_e32 v21, 0x1c00, v2
	ds_read2_b32 v[24:25], v21 offset0:56 offset1:188
	v_add_u32_e32 v33, 0x2000, v2
	ds_read2_b32 v[62:63], v33 offset0:64 offset1:196
	s_waitcnt lgkmcnt(2)
	v_add_f32_e32 v18, v16, v18
	v_add_f32_e32 v19, v18, v19
	v_add_f32_e32 v22, v19, v22
	v_add_f32_e32 v23, v22, v23
	s_waitcnt lgkmcnt(1)
	v_add_f32_e32 v24, v23, v24
	v_add_f32_e32 v25, v24, v25
	s_waitcnt lgkmcnt(0)
	v_add_f32_e32 v35, v25, v62
	v_add_u32_e32 v39, 0x2400, v2
	v_add_f32_e32 v37, v35, v63
	ds_read2_b32 v[62:63], v39 offset0:72 offset1:204
	v_add_u32_e32 v41, 0x2800, v2
	v_add_u32_e32 v64, 0x2c00, v2
	ds_read2_b32 v[66:67], v64 offset0:88 offset1:220
	v_add_u32_e32 v68, 0x3400, v2
	s_waitcnt lgkmcnt(1)
	v_add_f32_e32 v43, v37, v62
	v_add_f32_e32 v45, v43, v63
	ds_read2_b32 v[62:63], v41 offset0:80 offset1:212
	ds_read2_b32 v[72:73], v68 offset0:104 offset1:236
	v_add_u32_e32 v76, 0x3c00, v2
	ds_read2_b32 v[78:79], v76 offset0:120 offset1:252
	v_lshl_add_u32 v80, v80, 2, s71
	s_waitcnt lgkmcnt(2)
	v_add_f32_e32 v62, v45, v62
	v_add_f32_e32 v63, v62, v63
	v_add_f32_e32 v65, v63, v66
	v_add_f32_e32 v66, v65, v67
	v_add_u32_e32 v67, 0x3000, v2
	ds_read2_b32 v[70:71], v67 offset0:96 offset1:228
	s_waitcnt lgkmcnt(0)
	v_add_f32_e32 v69, v66, v70
	v_add_f32_e32 v70, v69, v71
	v_add_f32_e32 v71, v70, v72
	v_add_f32_e32 v72, v71, v73
	v_add_u32_e32 v73, 0x3800, v2
	ds_read2_b32 v[74:75], v73 offset0:112 offset1:244
	s_waitcnt lgkmcnt(0)
	v_add_f32_e32 v74, v72, v74
	v_add_f32_e32 v75, v74, v75
	v_add_f32_e32 v77, v75, v78
	v_add_f32_e32 v78, v77, v79
	s_and_saveexec_b64 s[0:1], s[46:47]
	ds_write_b32 v80, v78
	s_or_b64 exec, exec, s[0:1]
	v_mov_b32_e32 v79, 0
	s_waitcnt lgkmcnt(0)
	s_barrier
; #define BIDX (opaque_bid() * 2 + HALF_)
; __device__ __forceinline__ void hg_bcum(const Params& p, int l, const u16* Uhg, int t0, int h, float* bc, float* lbs,
;                                         float* tots) {
;     ...
;     __syncthreads();
;     const float add = hf ? tots[d] : 0.f;
; #pragma unroll
;     for (int s = 0; s < 32; ++s) bc[(hf * 32 + s) * BCS + d] = r[s] + add;
;   }
;   __syncthreads();
; }
; __device__ __forceinline__ void phase_hg_local(const Params& p, int l, char* smem) {
;   const u16* Uhg = (const u16*)(p.ws + OFF_UHG);
;   u16* states = (u16*)(p.ws + OFF_STATES);
;   float* gdec = (float*)(p.ws + OFF_GDEC);
;   float* bc = (float*)smem;
;   float* lbs = (float*)(smem + 33792);
;   u16* KT = (u16*)(smem + 33792 + 512);
;   u16* VTs = (u16*)(smem + 33792 + 512 + 18432);
;   const int tid = TIDX, lane = tid & 63, wave = tid >> 6;
;   const int c16 = lane & 15, q = lane >> 4;
;   const int vb0_ = BIDX;
;   for (int k_ = 0; k_ < (1024 + VGRID - 1) / VGRID; ++k_) {
;     int it = vb0_ + k_ * VGRID;
;     if (it > 1023) it = 1023;
;     const int b = it >> 9, h = (it >> 7) & 3, c = it & 127;
;     const int t0 = b * SEQL + c * 64;
;     hg_bcum(p, l, Uhg, t0, h, bc, lbs, (float*)(smem + 71168));
;     {
;       const int d = tid & 127;
;       const float bl = bc[63 * BCS + d];
;       for (int idx = tid; idx < 64 * 128; idx += 256) {
;         const int s = idx >> 7;
;         const float bs = bc[s * BCS + d];
;         const float bp = s ? bc[(s - 1) * BCS + d] : 0.f;
;         const float kk = 1.0f - __expf(bs - bp);
;         KT[d * 72 + s] = f2bf(kk * __expf(bl - bs));
;         VTs[d * 72 + s] = Uhg[(size_t)(t0 + s) * 2048 + 1024 + h * 128 + d];
	s_and_saveexec_b64 s[0:1], s[44:45]
	ds_read_b32 v79, v80
	s_or_b64 exec, exec, s[0:1]
	s_waitcnt lgkmcnt(0)
	v_add_f32_e32 v4, v4, v79
	v_add_f32_e32 v5, v5, v79
	ds_write2_b32 v2, v4, v5 offset1:132
	v_add_f32_e32 v2, v6, v79
	v_add_f32_e32 v4, v7, v79
	ds_write2_b32 v3, v2, v4 offset0:8 offset1:140
	v_add_f32_e32 v2, v9, v79
	v_add_f32_e32 v3, v10, v79
	ds_write2_b32 v8, v2, v3 offset0:16 offset1:148
	v_add_f32_e32 v2, v13, v79
	v_add_f32_e32 v3, v14, v79
	ds_write2_b32 v11, v2, v3 offset0:24 offset1:156
	v_add_f32_e32 v2, v15, v79
	v_add_f32_e32 v3, v16, v79
	ds_write2_b32 v12, v2, v3 offset0:32 offset1:164
	v_add_f32_e32 v2, v18, v79
	v_add_f32_e32 v3, v19, v79
	ds_write2_b32 v17, v2, v3 offset0:40 offset1:172
	v_add_f32_e32 v2, v22, v79
	v_add_f32_e32 v3, v23, v79
	ds_write2_b32 v20, v2, v3 offset0:48 offset1:180
	v_add_f32_e32 v2, v24, v79
	v_add_f32_e32 v3, v25, v79
	ds_write2_b32 v21, v2, v3 offset0:56 offset1:188
	v_add_f32_e32 v2, v35, v79
	v_add_f32_e32 v3, v37, v79
	ds_write2_b32 v33, v2, v3 offset0:64 offset1:196
	v_add_f32_e32 v2, v43, v79
	v_add_f32_e32 v3, v45, v79
	ds_write2_b32 v39, v2, v3 offset0:72 offset1:204
	v_add_f32_e32 v2, v62, v79
	v_add_f32_e32 v3, v63, v79
	ds_write2_b32 v41, v2, v3 offset0:80 offset1:212
	v_add_f32_e32 v2, v65, v79
	v_add_f32_e32 v3, v66, v79
	ds_write2_b32 v64, v2, v3 offset0:88 offset1:220
	v_add_f32_e32 v2, v69, v79
	v_add_f32_e32 v3, v70, v79
	ds_write2_b32 v67, v2, v3 offset0:96 offset1:228
	v_add_f32_e32 v2, v71, v79
	v_add_f32_e32 v3, v72, v79
	ds_write2_b32 v68, v2, v3 offset0:104 offset1:236
	v_add_f32_e32 v2, v74, v79
	v_add_f32_e32 v3, v75, v79
	ds_write2_b32 v73, v2, v3 offset0:112 offset1:244
	v_add_f32_e32 v2, v77, v79
	v_add_f32_e32 v3, v78, v79
	ds_write2_b32 v76, v2, v3 offset0:120 offset1:252
	s_waitcnt lgkmcnt(0)
	s_barrier
	ds_read_b32 v4, v47 offset:33264
	s_min_i32 s1, s20, 0x3ff
	s_lshl_b32 s0, s10, 7
	s_lshl_b32 s10, s1, 4
	s_and_b32 s1, s1, 0x7f
	s_and_b32 s10, s10, 0xffffe000
	s_lshl_b32 s1, s1, 6
	s_lshl_b32 s58, s0, 1
	s_or_b32 s21, s10, s1
	v_lshl_add_u64 v[2:3], v[26:27], 0, s[58:59]
	s_mov_b64 s[0:1], 0
	v_mov_b32_e32 v5, v61
	v_mov_b32_e32 v6, v60
	v_mov_b32_e32 v7, v46
	v_add_u32_e32 v8, s21, v60
	v_ashrrev_i32_e32 v9, 31, v8
	v_lshlrev_b64 v[8:9], 12, v[8:9]
	v_lshl_add_u64 v[8:9], v[2:3], 0, v[8:9]
	s_mov_b32 s98, 0x2000
	s_mov_b32 s99, 0
	global_load_ushort v126, v[8:9], off offset:2048
	v_lshl_add_u64 v[8:9], v[8:9], 0, s[98:99]
	global_load_ushort v127, v[8:9], off offset:2048
	v_lshl_add_u64 v[8:9], v[8:9], 0, s[98:99]
	global_load_ushort v128, v[8:9], off offset:2048
	v_lshl_add_u64 v[8:9], v[8:9], 0, s[98:99]
	global_load_ushort v129, v[8:9], off offset:2048
	v_lshl_add_u64 v[8:9], v[8:9], 0, s[98:99]
	global_load_ushort v130, v[8:9], off offset:2048
	v_lshl_add_u64 v[8:9], v[8:9], 0, s[98:99]
	global_load_ushort v131, v[8:9], off offset:2048
	v_lshl_add_u64 v[8:9], v[8:9], 0, s[98:99]
	global_load_ushort v132, v[8:9], off offset:2048
	v_lshl_add_u64 v[8:9], v[8:9], 0, s[98:99]
	global_load_ushort v133, v[8:9], off offset:2048
	v_lshl_add_u64 v[8:9], v[8:9], 0, s[98:99]
	global_load_ushort v134, v[8:9], off offset:2048
	v_lshl_add_u64 v[8:9], v[8:9], 0, s[98:99]
	global_load_ushort v135, v[8:9], off offset:2048
	v_lshl_add_u64 v[8:9], v[8:9], 0, s[98:99]
	global_load_ushort v136, v[8:9], off offset:2048
	v_lshl_add_u64 v[8:9], v[8:9], 0, s[98:99]
	global_load_ushort v137, v[8:9], off offset:2048
	v_lshl_add_u64 v[8:9], v[8:9], 0, s[98:99]
	global_load_ushort v138, v[8:9], off offset:2048
	v_lshl_add_u64 v[8:9], v[8:9], 0, s[98:99]
	global_load_ushort v139, v[8:9], off offset:2048
	v_lshl_add_u64 v[8:9], v[8:9], 0, s[98:99]
	global_load_ushort v140, v[8:9], off offset:2048
	v_lshl_add_u64 v[8:9], v[8:9], 0, s[98:99]
	global_load_ushort v141, v[8:9], off offset:2048
	v_lshl_add_u64 v[8:9], v[8:9], 0, s[98:99]
	global_load_ushort v142, v[8:9], off offset:2048
	v_lshl_add_u64 v[8:9], v[8:9], 0, s[98:99]
	global_load_ushort v143, v[8:9], off offset:2048
	v_lshl_add_u64 v[8:9], v[8:9], 0, s[98:99]
	global_load_ushort v144, v[8:9], off offset:2048
	v_lshl_add_u64 v[8:9], v[8:9], 0, s[98:99]
	global_load_ushort v145, v[8:9], off offset:2048
	v_lshl_add_u64 v[8:9], v[8:9], 0, s[98:99]
	global_load_ushort v146, v[8:9], off offset:2048
	v_lshl_add_u64 v[8:9], v[8:9], 0, s[98:99]
	global_load_ushort v147, v[8:9], off offset:2048
	v_lshl_add_u64 v[8:9], v[8:9], 0, s[98:99]
	global_load_ushort v148, v[8:9], off offset:2048
	v_lshl_add_u64 v[8:9], v[8:9], 0, s[98:99]
	global_load_ushort v149, v[8:9], off offset:2048
	v_lshl_add_u64 v[8:9], v[8:9], 0, s[98:99]
	global_load_ushort v150, v[8:9], off offset:2048
	v_lshl_add_u64 v[8:9], v[8:9], 0, s[98:99]
	global_load_ushort v151, v[8:9], off offset:2048
	v_lshl_add_u64 v[8:9], v[8:9], 0, s[98:99]
	global_load_ushort v152, v[8:9], off offset:2048
	v_lshl_add_u64 v[8:9], v[8:9], 0, s[98:99]
	global_load_ushort v153, v[8:9], off offset:2048
	v_lshl_add_u64 v[8:9], v[8:9], 0, s[98:99]
	global_load_ushort v154, v[8:9], off offset:2048
	v_lshl_add_u64 v[8:9], v[8:9], 0, s[98:99]
	global_load_ushort v155, v[8:9], off offset:2048
	v_lshl_add_u64 v[8:9], v[8:9], 0, s[98:99]
	global_load_ushort v156, v[8:9], off offset:2048
	v_lshl_add_u64 v[8:9], v[8:9], 0, s[98:99]
	global_load_ushort v157, v[8:9], off offset:2048
	s_branch .LBB0_387
